# E3 barrier + nt (non-temporal) hint on the read-once f32 weight loads of the weight-conversion loops and of the w_ada modulation stream
# speedup vs baseline: 1.0511x; 1.0205x over previous
.LBB0_441:
	s_lshl_b32 s10, s5, 1
	s_lshl_b32 s11, s4, 1
	v_add_u32_e32 v66, s10, v44
	v_add_u32_e32 v64, s11, v41
	v_add_u32_e32 v68, s11, v45
	v_add_u32_e32 v70, s10, v46
	v_add_u32_e32 v72, s11, v47
	v_add_u32_e32 v74, s10, v48
	v_add_u32_e32 v76, s11, v49
	v_add_u32_e32 v78, s10, v50
	v_add_u32_e32 v82, s11, v51
	v_add_u32_e32 v84, s10, v52
	v_add_u32_e32 v86, s11, v53
	v_add_u32_e32 v88, s10, v54
	v_add_u32_e32 v90, s11, v55
	v_add_u32_e32 v92, s10, v56
	v_add_u32_e32 v94, s11, v57
	v_add_u32_e32 v96, s10, v58
	v_ashrrev_i32_e32 v67, 31, v66
	v_ashrrev_i32_e32 v65, 31, v64
	v_ashrrev_i32_e32 v71, 31, v70
	v_ashrrev_i32_e32 v69, 31, v68
	v_ashrrev_i32_e32 v75, 31, v74
	v_ashrrev_i32_e32 v73, 31, v72
	v_ashrrev_i32_e32 v79, 31, v78
	v_ashrrev_i32_e32 v77, 31, v76
	v_ashrrev_i32_e32 v85, 31, v84
	v_ashrrev_i32_e32 v83, 31, v82
	v_ashrrev_i32_e32 v89, 31, v88
	v_ashrrev_i32_e32 v87, 31, v86
	v_ashrrev_i32_e32 v93, 31, v92
	v_ashrrev_i32_e32 v91, 31, v90
	v_ashrrev_i32_e32 v97, 31, v96
	v_ashrrev_i32_e32 v95, 31, v94
	v_lshlrev_b64 v[66:67], 12, v[66:67]
	v_lshlrev_b64 v[64:65], 12, v[64:65]
	v_lshlrev_b64 v[68:69], 12, v[68:69]
	v_lshlrev_b64 v[70:71], 12, v[70:71]
	v_lshlrev_b64 v[72:73], 12, v[72:73]
	v_lshlrev_b64 v[74:75], 12, v[74:75]
	v_lshlrev_b64 v[76:77], 12, v[76:77]
	v_lshlrev_b64 v[78:79], 12, v[78:79]
	v_lshlrev_b64 v[82:83], 12, v[82:83]
	v_lshlrev_b64 v[84:85], 12, v[84:85]
	v_lshlrev_b64 v[86:87], 12, v[86:87]
	v_lshlrev_b64 v[88:89], 12, v[88:89]
	v_lshlrev_b64 v[90:91], 12, v[90:91]
	v_lshlrev_b64 v[92:93], 12, v[92:93]
	v_lshlrev_b64 v[94:95], 12, v[94:95]
	v_lshlrev_b64 v[96:97], 12, v[96:97]
	v_lshl_add_u64 v[66:67], v[42:43], 0, v[66:67]
	v_lshl_add_u64 v[64:65], v[42:43], 0, v[64:65]
	v_lshl_add_u64 v[70:71], v[42:43], 0, v[70:71]
	v_lshl_add_u64 v[68:69], v[42:43], 0, v[68:69]
	v_lshl_add_u64 v[74:75], v[42:43], 0, v[74:75]
	v_lshl_add_u64 v[72:73], v[42:43], 0, v[72:73]
	v_lshl_add_u64 v[78:79], v[42:43], 0, v[78:79]
	v_lshl_add_u64 v[76:77], v[42:43], 0, v[76:77]
	v_lshl_add_u64 v[84:85], v[42:43], 0, v[84:85]
	v_lshl_add_u64 v[82:83], v[42:43], 0, v[82:83]
	v_lshl_add_u64 v[88:89], v[42:43], 0, v[88:89]
	v_lshl_add_u64 v[86:87], v[42:43], 0, v[86:87]
	v_lshl_add_u64 v[92:93], v[42:43], 0, v[92:93]
	v_lshl_add_u64 v[90:91], v[42:43], 0, v[90:91]
	v_lshl_add_u64 v[96:97], v[42:43], 0, v[96:97]
	v_lshl_add_u64 v[94:95], v[42:43], 0, v[94:95]
	global_load_dword v80, v[66:67], off nt
	global_load_dword v98, v[64:65], off nt
	global_load_dword v99, v[70:71], off nt
	global_load_dword v100, v[68:69], off nt
	global_load_dword v101, v[74:75], off nt
	global_load_dword v102, v[72:73], off nt
	global_load_dword v103, v[78:79], off nt
	global_load_dword v104, v[76:77], off nt
	global_load_dword v105, v[84:85], off nt
	global_load_dword v106, v[82:83], off nt
	global_load_dword v107, v[88:89], off nt
	global_load_dword v108, v[86:87], off nt
	global_load_dword v109, v[92:93], off nt
	global_load_dword v110, v[90:91], off nt
	global_load_dword v111, v[96:97], off nt
	global_load_dword v112, v[94:95], off nt
	s_add_i32 s5, s5, 16
	s_add_i32 s4, s4, 16
	s_add_i32 s9, s9, -16
	v_add_u32_e32 v64, s10, v0
	v_add_u32_e32 v66, s11, v1
	v_add_u32_e32 v70, s11, v3
	v_add_u32_e32 v68, s10, v28
	v_add_u32_e32 v74, s11, v29
	v_add_u32_e32 v72, s10, v30
	v_add_u32_e32 v78, s11, v31
	v_add_u32_e32 v76, s10, v32
	v_add_u32_e32 v84, s11, v33
	v_add_u32_e32 v82, s10, v34
	v_add_u32_e32 v88, s11, v35
	v_add_u32_e32 v86, s10, v36
	v_add_u32_e32 v92, s11, v37
	v_add_u32_e32 v90, s10, v38
	v_add_u32_e32 v96, s11, v39
	v_add_u32_e32 v94, s10, v40
	s_cmp_lg_u32 s9, 0
	v_mad_u64_u32 v[64:65], s[10:11], v64, s73, v[2:3]
	v_mad_u64_u32 v[66:67], s[10:11], v66, s73, v[2:3]
	v_mad_u64_u32 v[68:69], s[10:11], v68, s73, v[2:3]
	v_mad_u64_u32 v[70:71], s[10:11], v70, s73, v[2:3]
	v_mad_u64_u32 v[72:73], s[10:11], v72, s73, v[2:3]
	v_mad_u64_u32 v[74:75], s[10:11], v74, s73, v[2:3]
	v_mad_u64_u32 v[76:77], s[10:11], v76, s73, v[2:3]
	v_mad_u64_u32 v[78:79], s[10:11], v78, s73, v[2:3]
	v_mad_u64_u32 v[82:83], s[10:11], v82, s73, v[2:3]
	v_mad_u64_u32 v[84:85], s[10:11], v84, s73, v[2:3]
	v_mad_u64_u32 v[86:87], s[10:11], v86, s73, v[2:3]
	v_mad_u64_u32 v[88:89], s[10:11], v88, s73, v[2:3]
	v_mad_u64_u32 v[90:91], s[10:11], v90, s73, v[2:3]
	v_mad_u64_u32 v[92:93], s[10:11], v92, s73, v[2:3]
	v_mad_u64_u32 v[94:95], s[10:11], v94, s73, v[2:3]
	v_mad_u64_u32 v[96:97], s[10:11], v96, s73, v[2:3]
	s_waitcnt vmcnt(0)
	ds_write_b32 v64, v80
	ds_write_b32 v66, v98
	ds_write_b32 v68, v99
	ds_write_b32 v70, v100
	ds_write_b32 v72, v101
	ds_write_b32 v74, v102
	ds_write_b32 v76, v103
	ds_write_b32 v78, v104
	ds_write_b32 v82, v105
	ds_write_b32 v84, v106
	ds_write_b32 v86, v107
	ds_write_b32 v88, v108
	ds_write_b32 v90, v109
	ds_write_b32 v92, v110
	ds_write_b32 v94, v111
	ds_write_b32 v96, v112
	s_cbranch_scc1 .LBB0_441
	s_waitcnt lgkmcnt(0)
	ds_read2_b32 v[44:45], v60 offset1:33
	s_waitcnt lgkmcnt(0)
	v_cvt_pk_bf16_f32 v44, v44, v45
	ds_read2_b32 v[46:47], v60 offset0:66 offset1:99
	s_waitcnt lgkmcnt(0)
	v_cvt_pk_bf16_f32 v45, v46, v47
	ds_read2_b32 v[46:47], v60 offset0:132 offset1:165
	s_waitcnt lgkmcnt(0)
	v_cvt_pk_bf16_f32 v46, v46, v47
	ds_read2_b32 v[48:49], v60 offset0:198 offset1:231
	s_waitcnt lgkmcnt(0)
	v_cvt_pk_bf16_f32 v47, v48, v49
	v_add_u32_e32 v48, s0, v59
	s_lshl_b32 s18, s1, 1
	v_ashrrev_i32_e32 v49, 31, v48
	v_lshl_add_u64 v[42:43], v[4:5], 0, s[18:19]
	v_lshlrev_b64 v[48:49], 13, v[48:49]
	v_lshl_add_u64 v[48:49], v[42:43], 0, v[48:49]
	global_store_dwordx4 v[48:49], v[44:47], off
	ds_read2_b32 v[44:45], v60 offset0:8 offset1:41
	s_waitcnt lgkmcnt(0)
	v_cvt_pk_bf16_f32 v44, v44, v45
	ds_read2_b32 v[46:47], v60 offset0:74 offset1:107
	s_waitcnt lgkmcnt(0)
	v_cvt_pk_bf16_f32 v45, v46, v47
	ds_read2_b32 v[46:47], v60 offset0:140 offset1:173
	s_waitcnt lgkmcnt(0)
	v_cvt_pk_bf16_f32 v46, v46, v47
	ds_read2_b32 v[48:49], v60 offset0:206 offset1:239
	s_waitcnt lgkmcnt(0)
	v_cvt_pk_bf16_f32 v47, v48, v49
	v_add_u32_e32 v48, s0, v61
	v_ashrrev_i32_e32 v49, 31, v48
	v_lshlrev_b64 v[48:49], 13, v[48:49]
	v_lshl_add_u64 v[48:49], v[42:43], 0, v[48:49]
	global_store_dwordx4 v[48:49], v[44:47], off
	ds_read2_b32 v[44:45], v60 offset0:16 offset1:49
	s_waitcnt lgkmcnt(0)
	v_cvt_pk_bf16_f32 v44, v44, v45
	ds_read2_b32 v[46:47], v60 offset0:82 offset1:115
	s_waitcnt lgkmcnt(0)
	v_cvt_pk_bf16_f32 v45, v46, v47
	ds_read2_b32 v[46:47], v60 offset0:148 offset1:181
	s_waitcnt lgkmcnt(0)
	v_cvt_pk_bf16_f32 v46, v46, v47
	ds_read2_b32 v[48:49], v60 offset0:214 offset1:247
	s_waitcnt lgkmcnt(0)
	v_cvt_pk_bf16_f32 v47, v48, v49
	v_add_u32_e32 v48, s0, v62
	v_ashrrev_i32_e32 v49, 31, v48
	v_lshlrev_b64 v[48:49], 13, v[48:49]
	v_lshl_add_u64 v[48:49], v[42:43], 0, v[48:49]
	global_store_dwordx4 v[48:49], v[44:47], off
	ds_read2_b32 v[44:45], v60 offset0:24 offset1:57
	s_waitcnt lgkmcnt(0)
	v_cvt_pk_bf16_f32 v44, v44, v45
	ds_read2_b32 v[46:47], v60 offset0:90 offset1:123
	s_waitcnt lgkmcnt(0)
	v_cvt_pk_bf16_f32 v45, v46, v47
	ds_read2_b32 v[46:47], v60 offset0:156 offset1:189
	s_waitcnt lgkmcnt(0)
	v_cvt_pk_bf16_f32 v46, v46, v47
	ds_read2_b32 v[48:49], v60 offset0:222 offset1:255
	s_waitcnt lgkmcnt(0)
	v_cvt_pk_bf16_f32 v47, v48, v49
	v_add_u32_e32 v48, s0, v63
	v_ashrrev_i32_e32 v49, 31, v48
	v_lshlrev_b64 v[48:49], 13, v[48:49]
	v_lshl_add_u64 v[42:43], v[42:43], 0, v[48:49]
	global_store_dwordx4 v[42:43], v[44:47], off
	s_waitcnt lgkmcnt(0)
	s_mov_b64 s[0:1], 0

.LBB0_445:
	s_lshl_b32 s10, s5, 1
	s_lshl_b32 s11, s4, 1
	v_add_u32_e32 v66, s10, v44
	v_add_u32_e32 v64, s11, v41
	v_add_u32_e32 v68, s11, v45
	v_add_u32_e32 v70, s10, v46
	v_add_u32_e32 v72, s11, v47
	v_add_u32_e32 v74, s10, v48
	v_add_u32_e32 v76, s11, v49
	v_add_u32_e32 v78, s10, v50
	v_add_u32_e32 v82, s11, v51
	v_add_u32_e32 v84, s10, v52
	v_add_u32_e32 v86, s11, v53
	v_add_u32_e32 v88, s10, v54
	v_add_u32_e32 v90, s11, v55
	v_add_u32_e32 v92, s10, v56
	v_add_u32_e32 v94, s11, v57
	v_add_u32_e32 v96, s10, v58
	v_ashrrev_i32_e32 v67, 31, v66
	v_ashrrev_i32_e32 v65, 31, v64
	v_ashrrev_i32_e32 v71, 31, v70
	v_ashrrev_i32_e32 v69, 31, v68
	v_ashrrev_i32_e32 v75, 31, v74
	v_ashrrev_i32_e32 v73, 31, v72
	v_ashrrev_i32_e32 v79, 31, v78
	v_ashrrev_i32_e32 v77, 31, v76
	v_ashrrev_i32_e32 v85, 31, v84
	v_ashrrev_i32_e32 v83, 31, v82
	v_ashrrev_i32_e32 v89, 31, v88
	v_ashrrev_i32_e32 v87, 31, v86
	v_ashrrev_i32_e32 v93, 31, v92
	v_ashrrev_i32_e32 v91, 31, v90
	v_ashrrev_i32_e32 v97, 31, v96
	v_ashrrev_i32_e32 v95, 31, v94
	v_lshlrev_b64 v[66:67], 14, v[66:67]
	v_lshlrev_b64 v[64:65], 14, v[64:65]
	v_lshlrev_b64 v[68:69], 14, v[68:69]
	v_lshlrev_b64 v[70:71], 14, v[70:71]
	v_lshlrev_b64 v[72:73], 14, v[72:73]
	v_lshlrev_b64 v[74:75], 14, v[74:75]
	v_lshlrev_b64 v[76:77], 14, v[76:77]
	v_lshlrev_b64 v[78:79], 14, v[78:79]
	v_lshlrev_b64 v[82:83], 14, v[82:83]
	v_lshlrev_b64 v[84:85], 14, v[84:85]
	v_lshlrev_b64 v[86:87], 14, v[86:87]
	v_lshlrev_b64 v[88:89], 14, v[88:89]
	v_lshlrev_b64 v[90:91], 14, v[90:91]
	v_lshlrev_b64 v[92:93], 14, v[92:93]
	v_lshlrev_b64 v[94:95], 14, v[94:95]
	v_lshlrev_b64 v[96:97], 14, v[96:97]
	v_lshl_add_u64 v[66:67], v[42:43], 0, v[66:67]
	v_lshl_add_u64 v[64:65], v[42:43], 0, v[64:65]
	v_lshl_add_u64 v[70:71], v[42:43], 0, v[70:71]
	v_lshl_add_u64 v[68:69], v[42:43], 0, v[68:69]
	v_lshl_add_u64 v[74:75], v[42:43], 0, v[74:75]
	v_lshl_add_u64 v[72:73], v[42:43], 0, v[72:73]
	v_lshl_add_u64 v[78:79], v[42:43], 0, v[78:79]
	v_lshl_add_u64 v[76:77], v[42:43], 0, v[76:77]
	v_lshl_add_u64 v[84:85], v[42:43], 0, v[84:85]
	v_lshl_add_u64 v[82:83], v[42:43], 0, v[82:83]
	v_lshl_add_u64 v[88:89], v[42:43], 0, v[88:89]
	v_lshl_add_u64 v[86:87], v[42:43], 0, v[86:87]
	v_lshl_add_u64 v[92:93], v[42:43], 0, v[92:93]
	v_lshl_add_u64 v[90:91], v[42:43], 0, v[90:91]
	v_lshl_add_u64 v[96:97], v[42:43], 0, v[96:97]
	v_lshl_add_u64 v[94:95], v[42:43], 0, v[94:95]
	global_load_dword v80, v[66:67], off nt
	global_load_dword v98, v[64:65], off nt
	global_load_dword v99, v[70:71], off nt
	global_load_dword v100, v[68:69], off nt
	global_load_dword v101, v[74:75], off nt
	global_load_dword v102, v[72:73], off nt
	global_load_dword v103, v[78:79], off nt
	global_load_dword v104, v[76:77], off nt
	global_load_dword v105, v[84:85], off nt
	global_load_dword v106, v[82:83], off nt
	global_load_dword v107, v[88:89], off nt
	global_load_dword v108, v[86:87], off nt
	global_load_dword v109, v[92:93], off nt
	global_load_dword v110, v[90:91], off nt
	global_load_dword v111, v[96:97], off nt
	global_load_dword v112, v[94:95], off nt
	s_add_i32 s5, s5, 16
	s_add_i32 s4, s4, 16
	s_add_i32 s9, s9, -16
	v_add_u32_e32 v64, s10, v0
	v_add_u32_e32 v66, s11, v1
	v_add_u32_e32 v70, s11, v3
	v_add_u32_e32 v68, s10, v28
	v_add_u32_e32 v74, s11, v29
	v_add_u32_e32 v72, s10, v30
	v_add_u32_e32 v78, s11, v31
	v_add_u32_e32 v76, s10, v32
	v_add_u32_e32 v84, s11, v33
	v_add_u32_e32 v82, s10, v34
	v_add_u32_e32 v88, s11, v35
	v_add_u32_e32 v86, s10, v36
	v_add_u32_e32 v92, s11, v37
	v_add_u32_e32 v90, s10, v38
	v_add_u32_e32 v96, s11, v39
	v_add_u32_e32 v94, s10, v40
	s_cmp_lg_u32 s9, 0
	v_mad_u64_u32 v[64:65], s[10:11], v64, s73, v[2:3]
	v_mad_u64_u32 v[66:67], s[10:11], v66, s73, v[2:3]
	v_mad_u64_u32 v[68:69], s[10:11], v68, s73, v[2:3]
	v_mad_u64_u32 v[70:71], s[10:11], v70, s73, v[2:3]
	v_mad_u64_u32 v[72:73], s[10:11], v72, s73, v[2:3]
	v_mad_u64_u32 v[74:75], s[10:11], v74, s73, v[2:3]
	v_mad_u64_u32 v[76:77], s[10:11], v76, s73, v[2:3]
	v_mad_u64_u32 v[78:79], s[10:11], v78, s73, v[2:3]
	v_mad_u64_u32 v[82:83], s[10:11], v82, s73, v[2:3]
	v_mad_u64_u32 v[84:85], s[10:11], v84, s73, v[2:3]
	v_mad_u64_u32 v[86:87], s[10:11], v86, s73, v[2:3]
	v_mad_u64_u32 v[88:89], s[10:11], v88, s73, v[2:3]
	v_mad_u64_u32 v[90:91], s[10:11], v90, s73, v[2:3]
	v_mad_u64_u32 v[92:93], s[10:11], v92, s73, v[2:3]
	v_mad_u64_u32 v[94:95], s[10:11], v94, s73, v[2:3]
	v_mad_u64_u32 v[96:97], s[10:11], v96, s73, v[2:3]
	s_waitcnt vmcnt(0)
	ds_write_b32 v64, v80
	ds_write_b32 v66, v98
	ds_write_b32 v68, v99
	ds_write_b32 v70, v100
	ds_write_b32 v72, v101
	ds_write_b32 v74, v102
	ds_write_b32 v76, v103
	ds_write_b32 v78, v104
	ds_write_b32 v82, v105
	ds_write_b32 v84, v106
	ds_write_b32 v86, v107
	ds_write_b32 v88, v108
	ds_write_b32 v90, v109
	ds_write_b32 v92, v110
	ds_write_b32 v94, v111
	ds_write_b32 v96, v112
	s_cbranch_scc1 .LBB0_445
	s_waitcnt lgkmcnt(0)
	ds_read2_b32 v[44:45], v60 offset1:33
	s_waitcnt lgkmcnt(0)
	v_cvt_pk_bf16_f32 v44, v44, v45
	ds_read2_b32 v[46:47], v60 offset0:66 offset1:99
	s_waitcnt lgkmcnt(0)
	v_cvt_pk_bf16_f32 v45, v46, v47
	ds_read2_b32 v[46:47], v60 offset0:132 offset1:165
	s_waitcnt lgkmcnt(0)
	v_cvt_pk_bf16_f32 v46, v46, v47
	ds_read2_b32 v[48:49], v60 offset0:198 offset1:231
	s_waitcnt lgkmcnt(0)
	v_cvt_pk_bf16_f32 v47, v48, v49
	v_add_u32_e32 v48, s0, v59
	s_lshl_b32 s18, s1, 1
	v_ashrrev_i32_e32 v49, 31, v48
	v_lshl_add_u64 v[42:43], v[6:7], 0, s[18:19]
	v_lshlrev_b64 v[48:49], 11, v[48:49]
	v_lshl_add_u64 v[48:49], v[42:43], 0, v[48:49]
	global_store_dwordx4 v[48:49], v[44:47], off
	ds_read2_b32 v[44:45], v60 offset0:8 offset1:41
	s_waitcnt lgkmcnt(0)
	v_cvt_pk_bf16_f32 v44, v44, v45
	ds_read2_b32 v[46:47], v60 offset0:74 offset1:107
	s_waitcnt lgkmcnt(0)
	v_cvt_pk_bf16_f32 v45, v46, v47
	ds_read2_b32 v[46:47], v60 offset0:140 offset1:173
	s_waitcnt lgkmcnt(0)
	v_cvt_pk_bf16_f32 v46, v46, v47
	ds_read2_b32 v[48:49], v60 offset0:206 offset1:239
	s_waitcnt lgkmcnt(0)
	v_cvt_pk_bf16_f32 v47, v48, v49
	v_add_u32_e32 v48, s0, v61
	v_ashrrev_i32_e32 v49, 31, v48
	v_lshlrev_b64 v[48:49], 11, v[48:49]
	v_lshl_add_u64 v[48:49], v[42:43], 0, v[48:49]
	global_store_dwordx4 v[48:49], v[44:47], off
	ds_read2_b32 v[44:45], v60 offset0:16 offset1:49
	s_waitcnt lgkmcnt(0)
	v_cvt_pk_bf16_f32 v44, v44, v45
	ds_read2_b32 v[46:47], v60 offset0:82 offset1:115
	s_waitcnt lgkmcnt(0)
	v_cvt_pk_bf16_f32 v45, v46, v47
	ds_read2_b32 v[46:47], v60 offset0:148 offset1:181
	s_waitcnt lgkmcnt(0)
	v_cvt_pk_bf16_f32 v46, v46, v47
	ds_read2_b32 v[48:49], v60 offset0:214 offset1:247
	s_waitcnt lgkmcnt(0)
	v_cvt_pk_bf16_f32 v47, v48, v49
	v_add_u32_e32 v48, s0, v62
	v_ashrrev_i32_e32 v49, 31, v48
	v_lshlrev_b64 v[48:49], 11, v[48:49]
	v_lshl_add_u64 v[48:49], v[42:43], 0, v[48:49]
	global_store_dwordx4 v[48:49], v[44:47], off
	ds_read2_b32 v[44:45], v60 offset0:24 offset1:57
	s_waitcnt lgkmcnt(0)
	v_cvt_pk_bf16_f32 v44, v44, v45
	ds_read2_b32 v[46:47], v60 offset0:90 offset1:123
	s_waitcnt lgkmcnt(0)
	v_cvt_pk_bf16_f32 v45, v46, v47
	ds_read2_b32 v[46:47], v60 offset0:156 offset1:189
	s_waitcnt lgkmcnt(0)
	v_cvt_pk_bf16_f32 v46, v46, v47
	ds_read2_b32 v[48:49], v60 offset0:222 offset1:255
	s_waitcnt lgkmcnt(0)
	v_cvt_pk_bf16_f32 v47, v48, v49
	v_add_u32_e32 v48, s0, v63
	v_ashrrev_i32_e32 v49, 31, v48
	v_lshlrev_b64 v[48:49], 11, v[48:49]
	v_lshl_add_u64 v[42:43], v[42:43], 0, v[48:49]
	global_store_dwordx4 v[42:43], v[44:47], off
	s_waitcnt lgkmcnt(0)

.LBB0_450:
	s_lshl_b32 s10, s5, 1
	s_lshl_b32 s11, s4, 1
	v_add_u32_e32 v66, s10, v44
	v_add_u32_e32 v64, s11, v41
	v_add_u32_e32 v68, s11, v45
	v_add_u32_e32 v70, s10, v46
	v_add_u32_e32 v72, s11, v47
	v_add_u32_e32 v74, s10, v48
	v_add_u32_e32 v76, s11, v49
	v_add_u32_e32 v78, s10, v50
	v_add_u32_e32 v82, s11, v51
	v_add_u32_e32 v84, s10, v52
	v_add_u32_e32 v86, s11, v53
	v_add_u32_e32 v88, s10, v54
	v_add_u32_e32 v90, s11, v55
	v_add_u32_e32 v92, s10, v56
	v_add_u32_e32 v94, s11, v57
	v_add_u32_e32 v96, s10, v58
	v_ashrrev_i32_e32 v67, 31, v66
	v_ashrrev_i32_e32 v65, 31, v64
	v_ashrrev_i32_e32 v71, 31, v70
	v_ashrrev_i32_e32 v69, 31, v68
	v_ashrrev_i32_e32 v75, 31, v74
	v_ashrrev_i32_e32 v73, 31, v72
	v_ashrrev_i32_e32 v79, 31, v78
	v_ashrrev_i32_e32 v77, 31, v76
	v_ashrrev_i32_e32 v85, 31, v84
	v_ashrrev_i32_e32 v83, 31, v82
	v_ashrrev_i32_e32 v89, 31, v88
	v_ashrrev_i32_e32 v87, 31, v86
	v_ashrrev_i32_e32 v93, 31, v92
	v_ashrrev_i32_e32 v91, 31, v90
	v_ashrrev_i32_e32 v97, 31, v96
	v_ashrrev_i32_e32 v95, 31, v94
	v_lshlrev_b64 v[66:67], 12, v[66:67]
	v_lshlrev_b64 v[64:65], 12, v[64:65]
	v_lshlrev_b64 v[68:69], 12, v[68:69]
	v_lshlrev_b64 v[70:71], 12, v[70:71]
	v_lshlrev_b64 v[72:73], 12, v[72:73]
	v_lshlrev_b64 v[74:75], 12, v[74:75]
	v_lshlrev_b64 v[76:77], 12, v[76:77]
	v_lshlrev_b64 v[78:79], 12, v[78:79]
	v_lshlrev_b64 v[82:83], 12, v[82:83]
	v_lshlrev_b64 v[84:85], 12, v[84:85]
	v_lshlrev_b64 v[86:87], 12, v[86:87]
	v_lshlrev_b64 v[88:89], 12, v[88:89]
	v_lshlrev_b64 v[90:91], 12, v[90:91]
	v_lshlrev_b64 v[92:93], 12, v[92:93]
	v_lshlrev_b64 v[94:95], 12, v[94:95]
	v_lshlrev_b64 v[96:97], 12, v[96:97]
	v_lshl_add_u64 v[66:67], v[42:43], 0, v[66:67]
	v_lshl_add_u64 v[64:65], v[42:43], 0, v[64:65]
	v_lshl_add_u64 v[70:71], v[42:43], 0, v[70:71]
	v_lshl_add_u64 v[68:69], v[42:43], 0, v[68:69]
	v_lshl_add_u64 v[74:75], v[42:43], 0, v[74:75]
	v_lshl_add_u64 v[72:73], v[42:43], 0, v[72:73]
	v_lshl_add_u64 v[78:79], v[42:43], 0, v[78:79]
	v_lshl_add_u64 v[76:77], v[42:43], 0, v[76:77]
	v_lshl_add_u64 v[84:85], v[42:43], 0, v[84:85]
	v_lshl_add_u64 v[82:83], v[42:43], 0, v[82:83]
	v_lshl_add_u64 v[88:89], v[42:43], 0, v[88:89]
	v_lshl_add_u64 v[86:87], v[42:43], 0, v[86:87]
	v_lshl_add_u64 v[92:93], v[42:43], 0, v[92:93]
	v_lshl_add_u64 v[90:91], v[42:43], 0, v[90:91]
	v_lshl_add_u64 v[96:97], v[42:43], 0, v[96:97]
	v_lshl_add_u64 v[94:95], v[42:43], 0, v[94:95]
	global_load_dword v80, v[66:67], off nt
	global_load_dword v98, v[64:65], off nt
	global_load_dword v99, v[70:71], off nt
	global_load_dword v100, v[68:69], off nt
	global_load_dword v101, v[74:75], off nt
	global_load_dword v102, v[72:73], off nt
	global_load_dword v103, v[78:79], off nt
	global_load_dword v104, v[76:77], off nt
	global_load_dword v105, v[84:85], off nt
	global_load_dword v106, v[82:83], off nt
	global_load_dword v107, v[88:89], off nt
	global_load_dword v108, v[86:87], off nt
	global_load_dword v109, v[92:93], off nt
	global_load_dword v110, v[90:91], off nt
	global_load_dword v111, v[96:97], off nt
	global_load_dword v112, v[94:95], off nt
	s_add_i32 s5, s5, 16
	s_add_i32 s4, s4, 16
	s_add_i32 s9, s9, -16
	v_add_u32_e32 v64, s10, v0
	v_add_u32_e32 v66, s11, v1
	v_add_u32_e32 v70, s11, v3
	v_add_u32_e32 v68, s10, v28
	v_add_u32_e32 v74, s11, v29
	v_add_u32_e32 v72, s10, v30
	v_add_u32_e32 v78, s11, v31
	v_add_u32_e32 v76, s10, v32
	v_add_u32_e32 v84, s11, v33
	v_add_u32_e32 v82, s10, v34
	v_add_u32_e32 v88, s11, v35
	v_add_u32_e32 v86, s10, v36
	v_add_u32_e32 v92, s11, v37
	v_add_u32_e32 v90, s10, v38
	v_add_u32_e32 v96, s11, v39
	v_add_u32_e32 v94, s10, v40
	s_cmp_lg_u32 s9, 0
	v_mad_u64_u32 v[64:65], s[10:11], v64, s73, v[2:3]
	v_mad_u64_u32 v[66:67], s[10:11], v66, s73, v[2:3]
	v_mad_u64_u32 v[68:69], s[10:11], v68, s73, v[2:3]
	v_mad_u64_u32 v[70:71], s[10:11], v70, s73, v[2:3]
	v_mad_u64_u32 v[72:73], s[10:11], v72, s73, v[2:3]
	v_mad_u64_u32 v[74:75], s[10:11], v74, s73, v[2:3]
	v_mad_u64_u32 v[76:77], s[10:11], v76, s73, v[2:3]
	v_mad_u64_u32 v[78:79], s[10:11], v78, s73, v[2:3]
	v_mad_u64_u32 v[82:83], s[10:11], v82, s73, v[2:3]
	v_mad_u64_u32 v[84:85], s[10:11], v84, s73, v[2:3]
	v_mad_u64_u32 v[86:87], s[10:11], v86, s73, v[2:3]
	v_mad_u64_u32 v[88:89], s[10:11], v88, s73, v[2:3]
	v_mad_u64_u32 v[90:91], s[10:11], v90, s73, v[2:3]
	v_mad_u64_u32 v[92:93], s[10:11], v92, s73, v[2:3]
	v_mad_u64_u32 v[94:95], s[10:11], v94, s73, v[2:3]
	v_mad_u64_u32 v[96:97], s[10:11], v96, s73, v[2:3]
	s_waitcnt vmcnt(0)
	ds_write_b32 v64, v80
	ds_write_b32 v66, v98
	ds_write_b32 v68, v99
	ds_write_b32 v70, v100
	ds_write_b32 v72, v101
	ds_write_b32 v74, v102
	ds_write_b32 v76, v103
	ds_write_b32 v78, v104
	ds_write_b32 v82, v105
	ds_write_b32 v84, v106
	ds_write_b32 v86, v107
	ds_write_b32 v88, v108
	ds_write_b32 v90, v109
	ds_write_b32 v92, v110
	ds_write_b32 v94, v111
	ds_write_b32 v96, v112
	s_cbranch_scc1 .LBB0_450
	s_waitcnt lgkmcnt(0)
	ds_read2_b32 v[44:45], v60 offset1:33
	s_waitcnt lgkmcnt(0)
	v_cvt_pk_bf16_f32 v44, v44, v45
	ds_read2_b32 v[46:47], v60 offset0:66 offset1:99
	s_waitcnt lgkmcnt(0)
	v_cvt_pk_bf16_f32 v45, v46, v47
	ds_read2_b32 v[46:47], v60 offset0:132 offset1:165
	s_waitcnt lgkmcnt(0)
	v_cvt_pk_bf16_f32 v46, v46, v47
	ds_read2_b32 v[48:49], v60 offset0:198 offset1:231
	s_waitcnt lgkmcnt(0)
	v_cvt_pk_bf16_f32 v47, v48, v49
	v_add_u32_e32 v48, s0, v59
	s_lshl_b32 s18, s1, 1
	v_ashrrev_i32_e32 v49, 31, v48
	v_lshl_add_u64 v[42:43], v[8:9], 0, s[18:19]
	v_lshlrev_b64 v[48:49], 11, v[48:49]
	v_lshl_add_u64 v[48:49], v[42:43], 0, v[48:49]
	global_store_dwordx4 v[48:49], v[44:47], off
	ds_read2_b32 v[44:45], v60 offset0:8 offset1:41
	s_waitcnt lgkmcnt(0)
	v_cvt_pk_bf16_f32 v44, v44, v45
	ds_read2_b32 v[46:47], v60 offset0:74 offset1:107
	s_waitcnt lgkmcnt(0)
	v_cvt_pk_bf16_f32 v45, v46, v47
	ds_read2_b32 v[46:47], v60 offset0:140 offset1:173
	s_waitcnt lgkmcnt(0)
	v_cvt_pk_bf16_f32 v46, v46, v47
	ds_read2_b32 v[48:49], v60 offset0:206 offset1:239
	s_waitcnt lgkmcnt(0)
	v_cvt_pk_bf16_f32 v47, v48, v49
	v_add_u32_e32 v48, s0, v61
	v_ashrrev_i32_e32 v49, 31, v48
	v_lshlrev_b64 v[48:49], 11, v[48:49]
	v_lshl_add_u64 v[48:49], v[42:43], 0, v[48:49]
	global_store_dwordx4 v[48:49], v[44:47], off
	ds_read2_b32 v[44:45], v60 offset0:16 offset1:49
	s_waitcnt lgkmcnt(0)
	v_cvt_pk_bf16_f32 v44, v44, v45
	ds_read2_b32 v[46:47], v60 offset0:82 offset1:115
	s_waitcnt lgkmcnt(0)
	v_cvt_pk_bf16_f32 v45, v46, v47
	ds_read2_b32 v[46:47], v60 offset0:148 offset1:181
	s_waitcnt lgkmcnt(0)
	v_cvt_pk_bf16_f32 v46, v46, v47
	ds_read2_b32 v[48:49], v60 offset0:214 offset1:247
	s_waitcnt lgkmcnt(0)
	v_cvt_pk_bf16_f32 v47, v48, v49
	v_add_u32_e32 v48, s0, v62
	v_ashrrev_i32_e32 v49, 31, v48
	v_lshlrev_b64 v[48:49], 11, v[48:49]
	v_lshl_add_u64 v[48:49], v[42:43], 0, v[48:49]
	global_store_dwordx4 v[48:49], v[44:47], off
	ds_read2_b32 v[44:45], v60 offset0:24 offset1:57
	s_waitcnt lgkmcnt(0)
	v_cvt_pk_bf16_f32 v44, v44, v45
	ds_read2_b32 v[46:47], v60 offset0:90 offset1:123
	s_waitcnt lgkmcnt(0)
	v_cvt_pk_bf16_f32 v45, v46, v47
	ds_read2_b32 v[46:47], v60 offset0:156 offset1:189
	s_waitcnt lgkmcnt(0)
	v_cvt_pk_bf16_f32 v46, v46, v47
	ds_read2_b32 v[48:49], v60 offset0:222 offset1:255
	s_waitcnt lgkmcnt(0)
	v_cvt_pk_bf16_f32 v47, v48, v49
	v_add_u32_e32 v48, s0, v63
	v_ashrrev_i32_e32 v49, 31, v48
	v_lshlrev_b64 v[48:49], 11, v[48:49]
	v_lshl_add_u64 v[42:43], v[42:43], 0, v[48:49]
	global_store_dwordx4 v[42:43], v[44:47], off
	s_waitcnt lgkmcnt(0)

.LBB0_455:
	s_lshl_b32 s10, s5, 1
	s_lshl_b32 s11, s4, 1
	v_add_u32_e32 v66, s10, v44
	v_add_u32_e32 v64, s11, v41
	v_add_u32_e32 v68, s11, v45
	v_add_u32_e32 v70, s10, v46
	v_add_u32_e32 v72, s11, v47
	v_add_u32_e32 v74, s10, v48
	v_add_u32_e32 v76, s11, v49
	v_add_u32_e32 v78, s10, v50
	v_add_u32_e32 v82, s11, v51
	v_add_u32_e32 v84, s10, v52
	v_add_u32_e32 v86, s11, v53
	v_add_u32_e32 v88, s10, v54
	v_add_u32_e32 v90, s11, v55
	v_add_u32_e32 v92, s10, v56
	v_add_u32_e32 v94, s11, v57
	v_add_u32_e32 v96, s10, v58
	v_ashrrev_i32_e32 v67, 31, v66
	v_ashrrev_i32_e32 v65, 31, v64
	v_ashrrev_i32_e32 v71, 31, v70
	v_ashrrev_i32_e32 v69, 31, v68
	v_ashrrev_i32_e32 v75, 31, v74
	v_ashrrev_i32_e32 v73, 31, v72
	v_ashrrev_i32_e32 v79, 31, v78
	v_ashrrev_i32_e32 v77, 31, v76
	v_ashrrev_i32_e32 v85, 31, v84
	v_ashrrev_i32_e32 v83, 31, v82
	v_ashrrev_i32_e32 v89, 31, v88
	v_ashrrev_i32_e32 v87, 31, v86
	v_ashrrev_i32_e32 v93, 31, v92
	v_ashrrev_i32_e32 v91, 31, v90
	v_ashrrev_i32_e32 v97, 31, v96
	v_ashrrev_i32_e32 v95, 31, v94
	v_lshlrev_b64 v[66:67], 12, v[66:67]
	v_lshlrev_b64 v[64:65], 12, v[64:65]
	v_lshlrev_b64 v[68:69], 12, v[68:69]
	v_lshlrev_b64 v[70:71], 12, v[70:71]
	v_lshlrev_b64 v[72:73], 12, v[72:73]
	v_lshlrev_b64 v[74:75], 12, v[74:75]
	v_lshlrev_b64 v[76:77], 12, v[76:77]
	v_lshlrev_b64 v[78:79], 12, v[78:79]
	v_lshlrev_b64 v[82:83], 12, v[82:83]
	v_lshlrev_b64 v[84:85], 12, v[84:85]
	v_lshlrev_b64 v[86:87], 12, v[86:87]
	v_lshlrev_b64 v[88:89], 12, v[88:89]
	v_lshlrev_b64 v[90:91], 12, v[90:91]
	v_lshlrev_b64 v[92:93], 12, v[92:93]
	v_lshlrev_b64 v[94:95], 12, v[94:95]
	v_lshlrev_b64 v[96:97], 12, v[96:97]
	v_lshl_add_u64 v[66:67], v[42:43], 0, v[66:67]
	v_lshl_add_u64 v[64:65], v[42:43], 0, v[64:65]
	v_lshl_add_u64 v[70:71], v[42:43], 0, v[70:71]
	v_lshl_add_u64 v[68:69], v[42:43], 0, v[68:69]
	v_lshl_add_u64 v[74:75], v[42:43], 0, v[74:75]
	v_lshl_add_u64 v[72:73], v[42:43], 0, v[72:73]
	v_lshl_add_u64 v[78:79], v[42:43], 0, v[78:79]
	v_lshl_add_u64 v[76:77], v[42:43], 0, v[76:77]
	v_lshl_add_u64 v[84:85], v[42:43], 0, v[84:85]
	v_lshl_add_u64 v[82:83], v[42:43], 0, v[82:83]
	v_lshl_add_u64 v[88:89], v[42:43], 0, v[88:89]
	v_lshl_add_u64 v[86:87], v[42:43], 0, v[86:87]
	v_lshl_add_u64 v[92:93], v[42:43], 0, v[92:93]
	v_lshl_add_u64 v[90:91], v[42:43], 0, v[90:91]
	v_lshl_add_u64 v[96:97], v[42:43], 0, v[96:97]
	v_lshl_add_u64 v[94:95], v[42:43], 0, v[94:95]
	global_load_dword v80, v[66:67], off nt
	global_load_dword v98, v[64:65], off nt
	global_load_dword v99, v[70:71], off nt
	global_load_dword v100, v[68:69], off nt
	global_load_dword v101, v[74:75], off nt
	global_load_dword v102, v[72:73], off nt
	global_load_dword v103, v[78:79], off nt
	global_load_dword v104, v[76:77], off nt
	global_load_dword v105, v[84:85], off nt
	global_load_dword v106, v[82:83], off nt
	global_load_dword v107, v[88:89], off nt
	global_load_dword v108, v[86:87], off nt
	global_load_dword v109, v[92:93], off nt
	global_load_dword v110, v[90:91], off nt
	global_load_dword v111, v[96:97], off nt
	global_load_dword v112, v[94:95], off nt
	s_add_i32 s5, s5, 16
	s_add_i32 s4, s4, 16
	s_add_i32 s9, s9, -16
	v_add_u32_e32 v64, s10, v0
	v_add_u32_e32 v66, s11, v1
	v_add_u32_e32 v70, s11, v3
	v_add_u32_e32 v68, s10, v28
	v_add_u32_e32 v74, s11, v29
	v_add_u32_e32 v72, s10, v30
	v_add_u32_e32 v78, s11, v31
	v_add_u32_e32 v76, s10, v32
	v_add_u32_e32 v84, s11, v33
	v_add_u32_e32 v82, s10, v34
	v_add_u32_e32 v88, s11, v35
	v_add_u32_e32 v86, s10, v36
	v_add_u32_e32 v92, s11, v37
	v_add_u32_e32 v90, s10, v38
	v_add_u32_e32 v96, s11, v39
	v_add_u32_e32 v94, s10, v40
	s_cmp_lg_u32 s9, 0
	v_mad_u64_u32 v[64:65], s[10:11], v64, s73, v[2:3]
	v_mad_u64_u32 v[66:67], s[10:11], v66, s73, v[2:3]
	v_mad_u64_u32 v[68:69], s[10:11], v68, s73, v[2:3]
	v_mad_u64_u32 v[70:71], s[10:11], v70, s73, v[2:3]
	v_mad_u64_u32 v[72:73], s[10:11], v72, s73, v[2:3]
	v_mad_u64_u32 v[74:75], s[10:11], v74, s73, v[2:3]
	v_mad_u64_u32 v[76:77], s[10:11], v76, s73, v[2:3]
	v_mad_u64_u32 v[78:79], s[10:11], v78, s73, v[2:3]
	v_mad_u64_u32 v[82:83], s[10:11], v82, s73, v[2:3]
	v_mad_u64_u32 v[84:85], s[10:11], v84, s73, v[2:3]
	v_mad_u64_u32 v[86:87], s[10:11], v86, s73, v[2:3]
	v_mad_u64_u32 v[88:89], s[10:11], v88, s73, v[2:3]
	v_mad_u64_u32 v[90:91], s[10:11], v90, s73, v[2:3]
	v_mad_u64_u32 v[92:93], s[10:11], v92, s73, v[2:3]
	v_mad_u64_u32 v[94:95], s[10:11], v94, s73, v[2:3]
	v_mad_u64_u32 v[96:97], s[10:11], v96, s73, v[2:3]
	s_waitcnt vmcnt(0)
	ds_write_b32 v64, v80
	ds_write_b32 v66, v98
	ds_write_b32 v68, v99
	ds_write_b32 v70, v100
	ds_write_b32 v72, v101
	ds_write_b32 v74, v102
	ds_write_b32 v76, v103
	ds_write_b32 v78, v104
	ds_write_b32 v82, v105
	ds_write_b32 v84, v106
	ds_write_b32 v86, v107
	ds_write_b32 v88, v108
	ds_write_b32 v90, v109
	ds_write_b32 v92, v110
	ds_write_b32 v94, v111
	ds_write_b32 v96, v112
	s_cbranch_scc1 .LBB0_455
	s_waitcnt lgkmcnt(0)
	ds_read2_b32 v[44:45], v60 offset1:33
	s_waitcnt lgkmcnt(0)
	v_cvt_pk_bf16_f32 v44, v44, v45
	ds_read2_b32 v[46:47], v60 offset0:66 offset1:99
	s_waitcnt lgkmcnt(0)
	v_cvt_pk_bf16_f32 v45, v46, v47
	ds_read2_b32 v[46:47], v60 offset0:132 offset1:165
	s_waitcnt lgkmcnt(0)
	v_cvt_pk_bf16_f32 v46, v46, v47
	ds_read2_b32 v[48:49], v60 offset0:198 offset1:231
	s_waitcnt lgkmcnt(0)
	v_cvt_pk_bf16_f32 v47, v48, v49
	v_add_u32_e32 v48, s0, v59
	s_lshl_b32 s18, s1, 1
	v_ashrrev_i32_e32 v49, 31, v48
	v_lshl_add_u64 v[42:43], v[10:11], 0, s[18:19]
	v_lshlrev_b64 v[48:49], 9, v[48:49]
	v_lshl_add_u64 v[48:49], v[42:43], 0, v[48:49]
	global_store_dwordx4 v[48:49], v[44:47], off
	ds_read2_b32 v[44:45], v60 offset0:8 offset1:41
	s_waitcnt lgkmcnt(0)
	v_cvt_pk_bf16_f32 v44, v44, v45
	ds_read2_b32 v[46:47], v60 offset0:74 offset1:107
	s_waitcnt lgkmcnt(0)
	v_cvt_pk_bf16_f32 v45, v46, v47
	ds_read2_b32 v[46:47], v60 offset0:140 offset1:173
	s_waitcnt lgkmcnt(0)
	v_cvt_pk_bf16_f32 v46, v46, v47
	ds_read2_b32 v[48:49], v60 offset0:206 offset1:239
	s_waitcnt lgkmcnt(0)
	v_cvt_pk_bf16_f32 v47, v48, v49
	v_add_u32_e32 v48, s0, v61
	v_ashrrev_i32_e32 v49, 31, v48
	v_lshlrev_b64 v[48:49], 9, v[48:49]
	v_lshl_add_u64 v[48:49], v[42:43], 0, v[48:49]
	global_store_dwordx4 v[48:49], v[44:47], off
	ds_read2_b32 v[44:45], v60 offset0:16 offset1:49
	s_waitcnt lgkmcnt(0)
	v_cvt_pk_bf16_f32 v44, v44, v45
	ds_read2_b32 v[46:47], v60 offset0:82 offset1:115
	s_waitcnt lgkmcnt(0)
	v_cvt_pk_bf16_f32 v45, v46, v47
	ds_read2_b32 v[46:47], v60 offset0:148 offset1:181
	s_waitcnt lgkmcnt(0)
	v_cvt_pk_bf16_f32 v46, v46, v47
	ds_read2_b32 v[48:49], v60 offset0:214 offset1:247
	s_waitcnt lgkmcnt(0)
	v_cvt_pk_bf16_f32 v47, v48, v49
	v_add_u32_e32 v48, s0, v62
	v_ashrrev_i32_e32 v49, 31, v48
	v_lshlrev_b64 v[48:49], 9, v[48:49]
	v_lshl_add_u64 v[48:49], v[42:43], 0, v[48:49]
	global_store_dwordx4 v[48:49], v[44:47], off
	ds_read2_b32 v[44:45], v60 offset0:24 offset1:57
	s_waitcnt lgkmcnt(0)
	v_cvt_pk_bf16_f32 v44, v44, v45
	ds_read2_b32 v[46:47], v60 offset0:90 offset1:123
	s_waitcnt lgkmcnt(0)
	v_cvt_pk_bf16_f32 v45, v46, v47
	ds_read2_b32 v[46:47], v60 offset0:156 offset1:189
	s_waitcnt lgkmcnt(0)
	v_cvt_pk_bf16_f32 v46, v46, v47
	ds_read2_b32 v[48:49], v60 offset0:222 offset1:255
	s_waitcnt lgkmcnt(0)
	v_cvt_pk_bf16_f32 v47, v48, v49
	v_add_u32_e32 v48, s0, v63
	v_ashrrev_i32_e32 v49, 31, v48
	v_lshlrev_b64 v[48:49], 9, v[48:49]
	v_lshl_add_u64 v[42:43], v[42:43], 0, v[48:49]
	global_store_dwordx4 v[42:43], v[44:47], off
	s_waitcnt lgkmcnt(0)

.LBB0_460:
	s_lshl_b32 s10, s9, 1
	s_lshl_b32 s11, s5, 1
	v_add_u32_e32 v64, s10, v44
	v_add_u32_e32 v66, s11, v41
	v_mad_i64_i32 v[64:65], s[14:15], v64, s28, v[42:43]
	v_mad_i64_i32 v[66:67], s[14:15], v66, s28, v[42:43]
	global_load_dword v70, v[64:65], off nt
	global_load_dword v71, v[66:67], off nt
	v_add_u32_e32 v69, s10, v0
	v_add_u32_e32 v68, s11, v1
	v_mad_u64_u32 v[64:65], s[14:15], v69, s73, v[2:3]
	v_mad_u64_u32 v[66:67], s[14:15], v68, s73, v[2:3]
	v_add_u32_e32 v69, s10, v28
	v_add_u32_e32 v68, s11, v3
	s_add_i32 s9, s9, 16
	s_add_i32 s5, s5, 16
	s_add_i32 s1, s1, -16
	s_cmp_lg_u32 s1, 0
	s_waitcnt vmcnt(0)
	ds_write_b32 v64, v70
	ds_write_b32 v66, v71
	v_add_u32_e32 v64, s10, v46
	v_add_u32_e32 v66, s11, v45
	v_mad_i64_i32 v[64:65], s[14:15], v64, s28, v[42:43]
	v_mad_i64_i32 v[66:67], s[14:15], v66, s28, v[42:43]
	global_load_dword v70, v[64:65], off nt
	global_load_dword v71, v[66:67], off nt
	v_mad_u64_u32 v[64:65], s[14:15], v69, s73, v[2:3]
	v_mad_u64_u32 v[66:67], s[14:15], v68, s73, v[2:3]
	v_add_u32_e32 v69, s10, v30
	v_add_u32_e32 v68, s11, v29
	s_waitcnt vmcnt(1)
	ds_write_b32 v64, v70
	s_waitcnt vmcnt(0)
	ds_write_b32 v66, v71
	v_add_u32_e32 v64, s10, v48
	v_add_u32_e32 v66, s11, v47
	v_mad_i64_i32 v[64:65], s[14:15], v64, s28, v[42:43]
	v_mad_i64_i32 v[66:67], s[14:15], v66, s28, v[42:43]
	global_load_dword v70, v[64:65], off nt
	global_load_dword v71, v[66:67], off nt
	v_mad_u64_u32 v[64:65], s[14:15], v69, s73, v[2:3]
	v_mad_u64_u32 v[66:67], s[14:15], v68, s73, v[2:3]
	v_add_u32_e32 v69, s10, v32
	v_add_u32_e32 v68, s11, v31
	s_waitcnt vmcnt(1)
	ds_write_b32 v64, v70
	s_waitcnt vmcnt(0)
	ds_write_b32 v66, v71
	v_add_u32_e32 v64, s10, v50
	v_add_u32_e32 v66, s11, v49
	v_mad_i64_i32 v[64:65], s[14:15], v64, s28, v[42:43]
	v_mad_i64_i32 v[66:67], s[14:15], v66, s28, v[42:43]
	global_load_dword v70, v[64:65], off nt
	global_load_dword v71, v[66:67], off nt
	v_mad_u64_u32 v[64:65], s[14:15], v69, s73, v[2:3]
	v_mad_u64_u32 v[66:67], s[14:15], v68, s73, v[2:3]
	v_add_u32_e32 v69, s10, v34
	v_add_u32_e32 v68, s11, v33
	s_waitcnt vmcnt(1)
	ds_write_b32 v64, v70
	s_waitcnt vmcnt(0)
	ds_write_b32 v66, v71
	v_add_u32_e32 v64, s10, v52
	v_add_u32_e32 v66, s11, v51
	v_mad_i64_i32 v[64:65], s[14:15], v64, s28, v[42:43]
	v_mad_i64_i32 v[66:67], s[14:15], v66, s28, v[42:43]
	global_load_dword v70, v[64:65], off nt
	global_load_dword v71, v[66:67], off nt
	v_mad_u64_u32 v[64:65], s[14:15], v69, s73, v[2:3]
	v_mad_u64_u32 v[66:67], s[14:15], v68, s73, v[2:3]
	v_add_u32_e32 v69, s10, v36
	v_add_u32_e32 v68, s11, v35
	s_waitcnt vmcnt(1)
	ds_write_b32 v64, v70
	s_waitcnt vmcnt(0)
	ds_write_b32 v66, v71
	v_add_u32_e32 v64, s10, v54
	v_add_u32_e32 v66, s11, v53
	v_mad_i64_i32 v[64:65], s[14:15], v64, s28, v[42:43]
	v_mad_i64_i32 v[66:67], s[14:15], v66, s28, v[42:43]
	global_load_dword v70, v[64:65], off nt
	global_load_dword v71, v[66:67], off nt
	v_mad_u64_u32 v[64:65], s[14:15], v69, s73, v[2:3]
	v_mad_u64_u32 v[66:67], s[14:15], v68, s73, v[2:3]
	v_add_u32_e32 v69, s10, v38
	v_add_u32_e32 v68, s11, v37
	s_waitcnt vmcnt(1)
	ds_write_b32 v64, v70
	s_waitcnt vmcnt(0)
	ds_write_b32 v66, v71
	v_add_u32_e32 v64, s10, v56
	v_add_u32_e32 v66, s11, v55
	v_mad_i64_i32 v[64:65], s[14:15], v64, s28, v[42:43]
	v_mad_i64_i32 v[66:67], s[14:15], v66, s28, v[42:43]
	global_load_dword v70, v[64:65], off nt
	global_load_dword v71, v[66:67], off nt
	v_mad_u64_u32 v[64:65], s[14:15], v69, s73, v[2:3]
	v_mad_u64_u32 v[66:67], s[14:15], v68, s73, v[2:3]
	v_add_u32_e32 v68, s11, v39
	v_add_u32_e32 v69, s10, v40
	s_waitcnt vmcnt(1)
	ds_write_b32 v64, v70
	s_waitcnt vmcnt(0)
	ds_write_b32 v66, v71
	v_add_u32_e32 v64, s10, v58
	v_add_u32_e32 v66, s11, v57
	v_mad_i64_i32 v[64:65], s[10:11], v64, s28, v[42:43]
	v_mad_i64_i32 v[66:67], s[10:11], v66, s28, v[42:43]
	global_load_dword v70, v[64:65], off nt
	global_load_dword v71, v[66:67], off nt
	v_mad_u64_u32 v[64:65], s[10:11], v69, s73, v[2:3]
	v_mad_u64_u32 v[66:67], s[10:11], v68, s73, v[2:3]
	s_waitcnt vmcnt(1)
	ds_write_b32 v64, v70
	s_waitcnt vmcnt(0)
	ds_write_b32 v66, v71
	s_cbranch_scc1 .LBB0_460
	s_waitcnt lgkmcnt(0)
	ds_read2_b32 v[42:43], v60 offset1:33
	s_lshl_b32 s18, s4, 1
	v_lshl_add_u64 v[46:47], v[12:13], 0, s[18:19]
	s_movk_i32 s1, 0x300
	s_waitcnt lgkmcnt(0)
	v_mul_f32_e32 v41, 0x3dd53b94, v42
	v_mul_f32_e32 v42, 0x3dd53b94, v43
	v_cvt_pk_bf16_f32 v42, v41, v42
	ds_read2_b32 v[44:45], v60 offset0:66 offset1:99
	s_waitcnt lgkmcnt(0)
	v_mul_f32_e32 v43, 0x3dd53b94, v45
	v_mul_f32_e32 v41, 0x3dd53b94, v44
	v_cvt_pk_bf16_f32 v43, v41, v43
	ds_read2_b32 v[44:45], v60 offset0:132 offset1:165
	s_waitcnt lgkmcnt(0)
	v_mul_f32_e32 v41, 0x3dd53b94, v44
	v_mul_f32_e32 v44, 0x3dd53b94, v45
	v_cvt_pk_bf16_f32 v44, v41, v44
	ds_read2_b32 v[48:49], v60 offset0:198 offset1:231
	s_waitcnt lgkmcnt(0)
	v_mul_f32_e32 v41, 0x3dd53b94, v48
	v_mul_f32_e32 v45, 0x3dd53b94, v49
	v_cvt_pk_bf16_f32 v45, v41, v45
	v_add_u32_e32 v41, s0, v59
	v_mad_i64_i32 v[48:49], s[4:5], v41, s1, v[46:47]
	global_store_dwordx4 v[48:49], v[42:45], off
	ds_read2_b32 v[42:43], v60 offset0:8 offset1:41
	s_waitcnt lgkmcnt(0)
	v_mul_f32_e32 v41, 0x3dd53b94, v42
	v_mul_f32_e32 v42, 0x3dd53b94, v43
	v_cvt_pk_bf16_f32 v42, v41, v42
	ds_read2_b32 v[44:45], v60 offset0:74 offset1:107
	s_waitcnt lgkmcnt(0)
	v_mul_f32_e32 v43, 0x3dd53b94, v45
	v_mul_f32_e32 v41, 0x3dd53b94, v44
	v_cvt_pk_bf16_f32 v43, v41, v43
	ds_read2_b32 v[44:45], v60 offset0:140 offset1:173
	s_waitcnt lgkmcnt(0)
	v_mul_f32_e32 v41, 0x3dd53b94, v44
	v_mul_f32_e32 v44, 0x3dd53b94, v45
	v_cvt_pk_bf16_f32 v44, v41, v44
	ds_read2_b32 v[48:49], v60 offset0:206 offset1:239
	s_waitcnt lgkmcnt(0)
	v_mul_f32_e32 v41, 0x3dd53b94, v48
	v_mul_f32_e32 v45, 0x3dd53b94, v49
	v_cvt_pk_bf16_f32 v45, v41, v45
	v_add_u32_e32 v41, s0, v61
	v_mad_i64_i32 v[48:49], s[4:5], v41, s1, v[46:47]
	global_store_dwordx4 v[48:49], v[42:45], off
	ds_read2_b32 v[42:43], v60 offset0:16 offset1:49
	s_waitcnt lgkmcnt(0)
	v_mul_f32_e32 v41, 0x3dd53b94, v42
	v_mul_f32_e32 v42, 0x3dd53b94, v43
	v_cvt_pk_bf16_f32 v42, v41, v42
	ds_read2_b32 v[44:45], v60 offset0:82 offset1:115
	s_waitcnt lgkmcnt(0)
	v_mul_f32_e32 v43, 0x3dd53b94, v45
	v_mul_f32_e32 v41, 0x3dd53b94, v44
	v_cvt_pk_bf16_f32 v43, v41, v43
	ds_read2_b32 v[44:45], v60 offset0:148 offset1:181
	s_waitcnt lgkmcnt(0)
	v_mul_f32_e32 v41, 0x3dd53b94, v44
	v_mul_f32_e32 v44, 0x3dd53b94, v45
	v_cvt_pk_bf16_f32 v44, v41, v44
	ds_read2_b32 v[48:49], v60 offset0:214 offset1:247
	s_waitcnt lgkmcnt(0)
	v_mul_f32_e32 v41, 0x3dd53b94, v48
	v_mul_f32_e32 v45, 0x3dd53b94, v49
	v_cvt_pk_bf16_f32 v45, v41, v45
	v_add_u32_e32 v41, s0, v62
	v_mad_i64_i32 v[48:49], s[4:5], v41, s1, v[46:47]
	global_store_dwordx4 v[48:49], v[42:45], off
	ds_read2_b32 v[42:43], v60 offset0:24 offset1:57
	s_waitcnt lgkmcnt(0)
	v_mul_f32_e32 v41, 0x3dd53b94, v42
	v_mul_f32_e32 v42, 0x3dd53b94, v43
	v_cvt_pk_bf16_f32 v42, v41, v42
	ds_read2_b32 v[44:45], v60 offset0:90 offset1:123
	s_waitcnt lgkmcnt(0)
	v_mul_f32_e32 v43, 0x3dd53b94, v45
	v_mul_f32_e32 v41, 0x3dd53b94, v44
	v_cvt_pk_bf16_f32 v43, v41, v43
	ds_read2_b32 v[44:45], v60 offset0:156 offset1:189
	s_waitcnt lgkmcnt(0)
	v_mul_f32_e32 v41, 0x3dd53b94, v44
	v_mul_f32_e32 v44, 0x3dd53b94, v45
	v_cvt_pk_bf16_f32 v44, v41, v44
	ds_read2_b32 v[48:49], v60 offset0:222 offset1:255
	s_waitcnt lgkmcnt(0)
	v_mul_f32_e32 v41, 0x3dd53b94, v48
	v_mul_f32_e32 v45, 0x3dd53b94, v49
	v_cvt_pk_bf16_f32 v45, v41, v45
	v_add_u32_e32 v41, s0, v63
	v_mad_i64_i32 v[46:47], s[0:1], v41, s1, v[46:47]
	global_store_dwordx4 v[46:47], v[42:45], off
	s_waitcnt lgkmcnt(0)

.LBB0_464:
	s_lshl_b32 s10, s5, 1
	s_lshl_b32 s11, s1, 1
	v_add_u32_e32 v64, s10, v44
	v_add_u32_e32 v66, s11, v41
	v_mad_i64_i32 v[64:65], s[14:15], v64, s76, v[42:43]
	v_mad_i64_i32 v[66:67], s[14:15], v66, s76, v[42:43]
	global_load_dword v70, v[64:65], off nt
	global_load_dword v71, v[66:67], off nt
	v_add_u32_e32 v69, s10, v0
	v_add_u32_e32 v68, s11, v1
	v_mad_u64_u32 v[64:65], s[14:15], v69, s73, v[2:3]
	v_mad_u64_u32 v[66:67], s[14:15], v68, s73, v[2:3]
	v_add_u32_e32 v69, s10, v28
	v_add_u32_e32 v68, s11, v3
	s_add_i32 s5, s5, 16
	s_add_i32 s1, s1, 16
	s_add_i32 s9, s9, -16
	s_cmp_lg_u32 s9, 0
	s_waitcnt vmcnt(0)
	ds_write_b32 v64, v70
	ds_write_b32 v66, v71
	v_add_u32_e32 v64, s10, v46
	v_add_u32_e32 v66, s11, v45
	v_mad_i64_i32 v[64:65], s[14:15], v64, s76, v[42:43]
	v_mad_i64_i32 v[66:67], s[14:15], v66, s76, v[42:43]
	global_load_dword v70, v[64:65], off nt
	global_load_dword v71, v[66:67], off nt
	v_mad_u64_u32 v[64:65], s[14:15], v69, s73, v[2:3]
	v_mad_u64_u32 v[66:67], s[14:15], v68, s73, v[2:3]
	v_add_u32_e32 v69, s10, v30
	v_add_u32_e32 v68, s11, v29
	s_waitcnt vmcnt(1)
	ds_write_b32 v64, v70
	s_waitcnt vmcnt(0)
	ds_write_b32 v66, v71
	v_add_u32_e32 v64, s10, v48
	v_add_u32_e32 v66, s11, v47
	v_mad_i64_i32 v[64:65], s[14:15], v64, s76, v[42:43]
	v_mad_i64_i32 v[66:67], s[14:15], v66, s76, v[42:43]
	global_load_dword v70, v[64:65], off nt
	global_load_dword v71, v[66:67], off nt
	v_mad_u64_u32 v[64:65], s[14:15], v69, s73, v[2:3]
	v_mad_u64_u32 v[66:67], s[14:15], v68, s73, v[2:3]
	v_add_u32_e32 v69, s10, v32
	v_add_u32_e32 v68, s11, v31
	s_waitcnt vmcnt(1)
	ds_write_b32 v64, v70
	s_waitcnt vmcnt(0)
	ds_write_b32 v66, v71
	v_add_u32_e32 v64, s10, v50
	v_add_u32_e32 v66, s11, v49
	v_mad_i64_i32 v[64:65], s[14:15], v64, s76, v[42:43]
	v_mad_i64_i32 v[66:67], s[14:15], v66, s76, v[42:43]
	global_load_dword v70, v[64:65], off nt
	global_load_dword v71, v[66:67], off nt
	v_mad_u64_u32 v[64:65], s[14:15], v69, s73, v[2:3]
	v_mad_u64_u32 v[66:67], s[14:15], v68, s73, v[2:3]
	v_add_u32_e32 v69, s10, v34
	v_add_u32_e32 v68, s11, v33
	s_waitcnt vmcnt(1)
	ds_write_b32 v64, v70
	s_waitcnt vmcnt(0)
	ds_write_b32 v66, v71
	v_add_u32_e32 v64, s10, v52
	v_add_u32_e32 v66, s11, v51
	v_mad_i64_i32 v[64:65], s[14:15], v64, s76, v[42:43]
	v_mad_i64_i32 v[66:67], s[14:15], v66, s76, v[42:43]
	global_load_dword v70, v[64:65], off nt
	global_load_dword v71, v[66:67], off nt
	v_mad_u64_u32 v[64:65], s[14:15], v69, s73, v[2:3]
	v_mad_u64_u32 v[66:67], s[14:15], v68, s73, v[2:3]
	v_add_u32_e32 v69, s10, v36
	v_add_u32_e32 v68, s11, v35
	s_waitcnt vmcnt(1)
	ds_write_b32 v64, v70
	s_waitcnt vmcnt(0)
	ds_write_b32 v66, v71
	v_add_u32_e32 v64, s10, v54
	v_add_u32_e32 v66, s11, v53
	v_mad_i64_i32 v[64:65], s[14:15], v64, s76, v[42:43]
	v_mad_i64_i32 v[66:67], s[14:15], v66, s76, v[42:43]
	global_load_dword v70, v[64:65], off nt
	global_load_dword v71, v[66:67], off nt
	v_mad_u64_u32 v[64:65], s[14:15], v69, s73, v[2:3]
	v_mad_u64_u32 v[66:67], s[14:15], v68, s73, v[2:3]
	v_add_u32_e32 v69, s10, v38
	v_add_u32_e32 v68, s11, v37
	s_waitcnt vmcnt(1)
	ds_write_b32 v64, v70
	s_waitcnt vmcnt(0)
	ds_write_b32 v66, v71
	v_add_u32_e32 v64, s10, v56
	v_add_u32_e32 v66, s11, v55
	v_mad_i64_i32 v[64:65], s[14:15], v64, s76, v[42:43]
	v_mad_i64_i32 v[66:67], s[14:15], v66, s76, v[42:43]
	global_load_dword v70, v[64:65], off nt
	global_load_dword v71, v[66:67], off nt
	v_mad_u64_u32 v[64:65], s[14:15], v69, s73, v[2:3]
	v_mad_u64_u32 v[66:67], s[14:15], v68, s73, v[2:3]
	v_add_u32_e32 v68, s11, v39
	v_add_u32_e32 v69, s10, v40
	s_waitcnt vmcnt(1)
	ds_write_b32 v64, v70
	s_waitcnt vmcnt(0)
	ds_write_b32 v66, v71
	v_add_u32_e32 v64, s10, v58
	v_add_u32_e32 v66, s11, v57
	v_mad_i64_i32 v[64:65], s[10:11], v64, s76, v[42:43]
	v_mad_i64_i32 v[66:67], s[10:11], v66, s76, v[42:43]
	global_load_dword v70, v[64:65], off nt
	global_load_dword v71, v[66:67], off nt
	v_mad_u64_u32 v[64:65], s[10:11], v69, s73, v[2:3]
	v_mad_u64_u32 v[66:67], s[10:11], v68, s73, v[2:3]
	s_waitcnt vmcnt(1)
	ds_write_b32 v64, v70
	s_waitcnt vmcnt(0)
	ds_write_b32 v66, v71
	s_cbranch_scc1 .LBB0_464
	s_waitcnt lgkmcnt(0)
	ds_read2_b32 v[44:45], v60 offset1:33
	s_waitcnt lgkmcnt(0)
	v_cvt_pk_bf16_f32 v44, v44, v45
	ds_read2_b32 v[46:47], v60 offset0:66 offset1:99
	s_waitcnt lgkmcnt(0)
	v_cvt_pk_bf16_f32 v45, v46, v47
	ds_read2_b32 v[46:47], v60 offset0:132 offset1:165
	s_waitcnt lgkmcnt(0)
	v_cvt_pk_bf16_f32 v46, v46, v47
	ds_read2_b32 v[48:49], v60 offset0:198 offset1:231
	s_waitcnt lgkmcnt(0)
	v_cvt_pk_bf16_f32 v47, v48, v49
	v_add_u32_e32 v48, s0, v59
	s_ashr_i32 s5, s4, 31
	v_ashrrev_i32_e32 v49, 31, v48
	v_lshl_add_u64 v[42:43], s[4:5], 1, v[14:15]
	v_lshlrev_b64 v[48:49], 11, v[48:49]
	v_lshl_add_u64 v[48:49], v[42:43], 0, v[48:49]
	global_store_dwordx4 v[48:49], v[44:47], off
	ds_read2_b32 v[44:45], v60 offset0:8 offset1:41
	s_waitcnt lgkmcnt(0)
	v_cvt_pk_bf16_f32 v44, v44, v45
	ds_read2_b32 v[46:47], v60 offset0:74 offset1:107
	s_waitcnt lgkmcnt(0)
	v_cvt_pk_bf16_f32 v45, v46, v47
	ds_read2_b32 v[46:47], v60 offset0:140 offset1:173
	s_waitcnt lgkmcnt(0)
	v_cvt_pk_bf16_f32 v46, v46, v47
	ds_read2_b32 v[48:49], v60 offset0:206 offset1:239
	s_waitcnt lgkmcnt(0)
	v_cvt_pk_bf16_f32 v47, v48, v49
	v_add_u32_e32 v48, s0, v61
	v_ashrrev_i32_e32 v49, 31, v48
	v_lshlrev_b64 v[48:49], 11, v[48:49]
	v_lshl_add_u64 v[48:49], v[42:43], 0, v[48:49]
	global_store_dwordx4 v[48:49], v[44:47], off
	ds_read2_b32 v[44:45], v60 offset0:16 offset1:49
	s_waitcnt lgkmcnt(0)
	v_cvt_pk_bf16_f32 v44, v44, v45
	ds_read2_b32 v[46:47], v60 offset0:82 offset1:115
	s_waitcnt lgkmcnt(0)
	v_cvt_pk_bf16_f32 v45, v46, v47
	ds_read2_b32 v[46:47], v60 offset0:148 offset1:181
	s_waitcnt lgkmcnt(0)
	v_cvt_pk_bf16_f32 v46, v46, v47
	ds_read2_b32 v[48:49], v60 offset0:214 offset1:247
	s_waitcnt lgkmcnt(0)
	v_cvt_pk_bf16_f32 v47, v48, v49
	v_add_u32_e32 v48, s0, v62
	v_ashrrev_i32_e32 v49, 31, v48
	v_lshlrev_b64 v[48:49], 11, v[48:49]
	v_lshl_add_u64 v[48:49], v[42:43], 0, v[48:49]
	global_store_dwordx4 v[48:49], v[44:47], off
	ds_read2_b32 v[44:45], v60 offset0:24 offset1:57
	s_waitcnt lgkmcnt(0)
	v_cvt_pk_bf16_f32 v44, v44, v45
	ds_read2_b32 v[46:47], v60 offset0:90 offset1:123
	s_waitcnt lgkmcnt(0)
	v_cvt_pk_bf16_f32 v45, v46, v47
	ds_read2_b32 v[46:47], v60 offset0:156 offset1:189
	s_waitcnt lgkmcnt(0)
	v_cvt_pk_bf16_f32 v46, v46, v47
	ds_read2_b32 v[48:49], v60 offset0:222 offset1:255
	s_waitcnt lgkmcnt(0)
	v_cvt_pk_bf16_f32 v47, v48, v49
	v_add_u32_e32 v48, s0, v63
	v_ashrrev_i32_e32 v49, 31, v48
	v_lshlrev_b64 v[48:49], 11, v[48:49]
	v_lshl_add_u64 v[42:43], v[42:43], 0, v[48:49]
	global_store_dwordx4 v[42:43], v[44:47], off
	s_waitcnt lgkmcnt(0)
	s_branch .LBB0_433

.LBB0_534:
	v_lshl_add_u64 v[20:21], v[2:3], 0, s[6:7]
	s_movk_i32 s5, 0x6000
	v_add_co_u32_e32 v22, vcc, s5, v20
	s_mov_b32 s5, 0xc000
	s_nop 0
	v_addc_co_u32_e32 v23, vcc, 0, v21, vcc
	v_add_co_u32_e32 v24, vcc, s5, v20
	s_mov_b32 s5, 0x12000
	s_nop 0
	v_addc_co_u32_e32 v25, vcc, 0, v21, vcc
	v_add_co_u32_e32 v26, vcc, s5, v20
	s_mov_b32 s5, 0x18000
	s_nop 0
	v_addc_co_u32_e32 v27, vcc, 0, v21, vcc
	global_load_dwordx2 v[14:15], v[20:21], off nt
	v_add_co_u32_e32 v28, vcc, s5, v20
	s_mov_b32 s5, 0x1e000
	s_nop 0
	v_addc_co_u32_e32 v29, vcc, 0, v21, vcc
	v_add_co_u32_e32 v30, vcc, s5, v20
	s_mov_b32 s5, 0x24000
	s_nop 0
	v_addc_co_u32_e32 v31, vcc, 0, v21, vcc
	v_add_co_u32_e32 v32, vcc, s5, v20
	s_mov_b32 s5, 0x2a000
	s_nop 0
	v_addc_co_u32_e32 v33, vcc, 0, v21, vcc
	v_add_co_u32_e32 v20, vcc, s5, v20
	v_mov_b32_e32 v56, s1
	s_nop 0
	v_addc_co_u32_e32 v21, vcc, 0, v21, vcc
	global_load_dwordx2 v[60:61], v[22:23], off nt
	global_load_dwordx2 v[62:63], v[24:25], off nt
	global_load_dwordx2 v[64:65], v[26:27], off nt
	global_load_dwordx2 v[66:67], v[28:29], off nt
	global_load_dwordx2 v[68:69], v[30:31], off nt
	global_load_dwordx2 v[70:71], v[32:33], off nt
	global_load_dwordx2 v[72:73], v[20:21], off nt
	ds_read_b128 v[20:23], v56
	ds_read_b128 v[24:27], v56 offset:16
	ds_read_b128 v[28:31], v56 offset:4096
	ds_read_b128 v[32:35], v56 offset:4112
	ds_read_b128 v[36:39], v56 offset:8192
	ds_read_b128 v[40:43], v56 offset:8208
	ds_read_b128 v[44:47], v56 offset:12288
	ds_read_b128 v[48:51], v56 offset:12304
	ds_read_b128 v[52:55], v56 offset:16384
	ds_read_b128 v[56:59], v56 offset:16400
	s_waitcnt lgkmcnt(9)
	v_mov_b32_e32 v74, v23
	s_waitcnt lgkmcnt(7)
	v_mov_b32_e32 v76, v31
	s_waitcnt lgkmcnt(5)
	v_mov_b32_e32 v78, v39
	s_waitcnt lgkmcnt(3)
	v_mov_b32_e32 v80, v47
	s_waitcnt lgkmcnt(1)
	v_mov_b32_e32 v82, v55
	s_add_u32 s6, s6, 0x30000
	s_addc_u32 s7, s7, 0
	s_add_i32 s1, s1, 32
	v_mov_b32_e32 v84, v27
	v_mov_b32_e32 v86, v35
	v_mov_b32_e32 v88, v43
	v_mov_b32_e32 v90, v51
	s_waitcnt lgkmcnt(0)
	v_mov_b32_e32 v92, v59
	s_cmp_eq_u32 s6, 0x300000
	s_waitcnt vmcnt(7)
	v_pk_fma_f32 v[4:5], v[14:15], v[20:21], v[4:5] op_sel_hi:[1,0,1]
	v_pk_fma_f32 v[8:9], v[14:15], v[28:29], v[8:9] op_sel_hi:[1,0,1]
	v_pk_fma_f32 v[6:7], v[14:15], v[36:37], v[6:7] op_sel_hi:[1,0,1]
	v_pk_fma_f32 v[12:13], v[14:15], v[44:45], v[12:13] op_sel_hi:[1,0,1]
	v_pk_fma_f32 v[10:11], v[14:15], v[52:53], v[10:11] op_sel_hi:[1,0,1]
	s_waitcnt vmcnt(6)
	v_pk_fma_f32 v[4:5], v[60:61], v[20:21], v[4:5] op_sel:[0,1,0]
	v_pk_fma_f32 v[8:9], v[60:61], v[28:29], v[8:9] op_sel:[0,1,0]
	v_pk_fma_f32 v[6:7], v[60:61], v[36:37], v[6:7] op_sel:[0,1,0]
	v_pk_fma_f32 v[12:13], v[60:61], v[44:45], v[12:13] op_sel:[0,1,0]
	v_pk_fma_f32 v[10:11], v[60:61], v[52:53], v[10:11] op_sel:[0,1,0]
	s_waitcnt vmcnt(5)
	v_pk_fma_f32 v[4:5], v[62:63], v[22:23], v[4:5] op_sel_hi:[1,0,1]
	v_pk_fma_f32 v[8:9], v[62:63], v[30:31], v[8:9] op_sel_hi:[1,0,1]
	v_pk_fma_f32 v[6:7], v[62:63], v[38:39], v[6:7] op_sel_hi:[1,0,1]
	v_pk_fma_f32 v[12:13], v[62:63], v[46:47], v[12:13] op_sel_hi:[1,0,1]
	v_pk_fma_f32 v[10:11], v[62:63], v[54:55], v[10:11] op_sel_hi:[1,0,1]
	s_waitcnt vmcnt(4)
	v_pk_fma_f32 v[4:5], v[64:65], v[74:75], v[4:5] op_sel_hi:[1,0,1]
	v_pk_fma_f32 v[8:9], v[64:65], v[76:77], v[8:9] op_sel_hi:[1,0,1]
	v_pk_fma_f32 v[6:7], v[64:65], v[78:79], v[6:7] op_sel_hi:[1,0,1]
	v_pk_fma_f32 v[12:13], v[64:65], v[80:81], v[12:13] op_sel_hi:[1,0,1]
	v_pk_fma_f32 v[10:11], v[64:65], v[82:83], v[10:11] op_sel_hi:[1,0,1]
	s_waitcnt vmcnt(3)
	v_pk_fma_f32 v[4:5], v[66:67], v[24:25], v[4:5] op_sel_hi:[1,0,1]
	v_pk_fma_f32 v[8:9], v[66:67], v[32:33], v[8:9] op_sel_hi:[1,0,1]
	v_pk_fma_f32 v[6:7], v[66:67], v[40:41], v[6:7] op_sel_hi:[1,0,1]
	v_pk_fma_f32 v[12:13], v[66:67], v[48:49], v[12:13] op_sel_hi:[1,0,1]
	v_pk_fma_f32 v[10:11], v[66:67], v[56:57], v[10:11] op_sel_hi:[1,0,1]
	s_waitcnt vmcnt(2)
	v_pk_fma_f32 v[4:5], v[68:69], v[24:25], v[4:5] op_sel:[0,1,0]
	v_pk_fma_f32 v[8:9], v[68:69], v[32:33], v[8:9] op_sel:[0,1,0]
	v_pk_fma_f32 v[6:7], v[68:69], v[40:41], v[6:7] op_sel:[0,1,0]
	v_pk_fma_f32 v[12:13], v[68:69], v[48:49], v[12:13] op_sel:[0,1,0]
	v_pk_fma_f32 v[10:11], v[68:69], v[56:57], v[10:11] op_sel:[0,1,0]
	s_waitcnt vmcnt(1)
	v_pk_fma_f32 v[4:5], v[70:71], v[26:27], v[4:5] op_sel_hi:[1,0,1]
	v_pk_fma_f32 v[8:9], v[70:71], v[34:35], v[8:9] op_sel_hi:[1,0,1]
	v_pk_fma_f32 v[6:7], v[70:71], v[42:43], v[6:7] op_sel_hi:[1,0,1]
	v_pk_fma_f32 v[12:13], v[70:71], v[50:51], v[12:13] op_sel_hi:[1,0,1]
	v_pk_fma_f32 v[10:11], v[70:71], v[58:59], v[10:11] op_sel_hi:[1,0,1]
	s_waitcnt vmcnt(0)
	v_pk_fma_f32 v[4:5], v[72:73], v[84:85], v[4:5] op_sel_hi:[1,0,1]
	v_pk_fma_f32 v[8:9], v[72:73], v[86:87], v[8:9] op_sel_hi:[1,0,1]
	v_pk_fma_f32 v[6:7], v[72:73], v[88:89], v[6:7] op_sel_hi:[1,0,1]
	v_pk_fma_f32 v[12:13], v[72:73], v[90:91], v[12:13] op_sel_hi:[1,0,1]
	v_pk_fma_f32 v[10:11], v[72:73], v[92:93], v[10:11] op_sel_hi:[1,0,1]
	s_cbranch_scc0 .LBB0_534
	ds_write2st64_b64 v18, v[4:5], v[8:9] offset0:64 offset1:65
	ds_write2st64_b64 v18, v[6:7], v[12:13] offset0:66 offset1:67
	ds_write_b64 v18, v[10:11] offset:34816
	s_waitcnt lgkmcnt(0)
	s_barrier
	s_and_saveexec_b64 s[6:7], s[38:39]
	s_cbranch_execz .LBB0_525
	s_mul_i32 s1, s4, 0x1800
	s_mul_i32 s10, s4, 5
	s_mov_b64 s[4:5], 0
	v_mov_b32_e32 v2, v17

.LBB0_548:
	s_lshl_b32 s9, s5, 1
	s_lshl_b32 s10, s4, 1
	v_add_u32_e32 v66, s9, v44
	v_add_u32_e32 v64, s10, v41
	v_add_u32_e32 v68, s10, v45
	v_add_u32_e32 v70, s9, v46
	v_add_u32_e32 v72, s10, v47
	v_add_u32_e32 v74, s9, v48
	v_add_u32_e32 v76, s10, v49
	v_add_u32_e32 v78, s9, v50
	v_add_u32_e32 v82, s10, v51
	v_add_u32_e32 v84, s9, v52
	v_add_u32_e32 v86, s10, v53
	v_add_u32_e32 v88, s9, v54
	v_add_u32_e32 v90, s10, v55
	v_add_u32_e32 v92, s9, v56
	v_add_u32_e32 v94, s10, v57
	v_add_u32_e32 v96, s9, v58
	v_ashrrev_i32_e32 v67, 31, v66
	v_ashrrev_i32_e32 v65, 31, v64
	v_ashrrev_i32_e32 v71, 31, v70
	v_ashrrev_i32_e32 v69, 31, v68
	v_ashrrev_i32_e32 v75, 31, v74
	v_ashrrev_i32_e32 v73, 31, v72
	v_ashrrev_i32_e32 v79, 31, v78
	v_ashrrev_i32_e32 v77, 31, v76
	v_ashrrev_i32_e32 v85, 31, v84
	v_ashrrev_i32_e32 v83, 31, v82
	v_ashrrev_i32_e32 v89, 31, v88
	v_ashrrev_i32_e32 v87, 31, v86
	v_ashrrev_i32_e32 v93, 31, v92
	v_ashrrev_i32_e32 v91, 31, v90
	v_ashrrev_i32_e32 v97, 31, v96
	v_ashrrev_i32_e32 v95, 31, v94
	v_lshlrev_b64 v[66:67], 12, v[66:67]
	v_lshlrev_b64 v[64:65], 12, v[64:65]
	v_lshlrev_b64 v[68:69], 12, v[68:69]
	v_lshlrev_b64 v[70:71], 12, v[70:71]
	v_lshlrev_b64 v[72:73], 12, v[72:73]
	v_lshlrev_b64 v[74:75], 12, v[74:75]
	v_lshlrev_b64 v[76:77], 12, v[76:77]
	v_lshlrev_b64 v[78:79], 12, v[78:79]
	v_lshlrev_b64 v[82:83], 12, v[82:83]
	v_lshlrev_b64 v[84:85], 12, v[84:85]
	v_lshlrev_b64 v[86:87], 12, v[86:87]
	v_lshlrev_b64 v[88:89], 12, v[88:89]
	v_lshlrev_b64 v[90:91], 12, v[90:91]
	v_lshlrev_b64 v[92:93], 12, v[92:93]
	v_lshlrev_b64 v[94:95], 12, v[94:95]
	v_lshlrev_b64 v[96:97], 12, v[96:97]
	v_lshl_add_u64 v[66:67], v[42:43], 0, v[66:67]
	v_lshl_add_u64 v[64:65], v[42:43], 0, v[64:65]
	v_lshl_add_u64 v[70:71], v[42:43], 0, v[70:71]
	v_lshl_add_u64 v[68:69], v[42:43], 0, v[68:69]
	v_lshl_add_u64 v[74:75], v[42:43], 0, v[74:75]
	v_lshl_add_u64 v[72:73], v[42:43], 0, v[72:73]
	v_lshl_add_u64 v[78:79], v[42:43], 0, v[78:79]
	v_lshl_add_u64 v[76:77], v[42:43], 0, v[76:77]
	v_lshl_add_u64 v[84:85], v[42:43], 0, v[84:85]
	v_lshl_add_u64 v[82:83], v[42:43], 0, v[82:83]
	v_lshl_add_u64 v[88:89], v[42:43], 0, v[88:89]
	v_lshl_add_u64 v[86:87], v[42:43], 0, v[86:87]
	v_lshl_add_u64 v[92:93], v[42:43], 0, v[92:93]
	v_lshl_add_u64 v[90:91], v[42:43], 0, v[90:91]
	v_lshl_add_u64 v[96:97], v[42:43], 0, v[96:97]
	v_lshl_add_u64 v[94:95], v[42:43], 0, v[94:95]
	global_load_dword v80, v[66:67], off nt
	global_load_dword v98, v[64:65], off nt
	global_load_dword v99, v[70:71], off nt
	global_load_dword v100, v[68:69], off nt
	global_load_dword v101, v[74:75], off nt
	global_load_dword v102, v[72:73], off nt
	global_load_dword v103, v[78:79], off nt
	global_load_dword v104, v[76:77], off nt
	global_load_dword v105, v[84:85], off nt
	global_load_dword v106, v[82:83], off nt
	global_load_dword v107, v[88:89], off nt
	global_load_dword v108, v[86:87], off nt
	global_load_dword v109, v[92:93], off nt
	global_load_dword v110, v[90:91], off nt
	global_load_dword v111, v[96:97], off nt
	global_load_dword v112, v[94:95], off nt
	s_add_i32 s5, s5, 16
	s_add_i32 s4, s4, 16
	s_add_i32 s8, s8, -16
	v_add_u32_e32 v64, s9, v0
	v_add_u32_e32 v66, s10, v1
	v_add_u32_e32 v70, s10, v3
	v_add_u32_e32 v68, s9, v28
	v_add_u32_e32 v74, s10, v29
	v_add_u32_e32 v72, s9, v30
	v_add_u32_e32 v78, s10, v31
	v_add_u32_e32 v76, s9, v32
	v_add_u32_e32 v84, s10, v33
	v_add_u32_e32 v82, s9, v34
	v_add_u32_e32 v88, s10, v35
	v_add_u32_e32 v86, s9, v36
	v_add_u32_e32 v92, s10, v37
	v_add_u32_e32 v90, s9, v38
	v_add_u32_e32 v96, s10, v39
	v_add_u32_e32 v94, s9, v40
	s_cmp_lg_u32 s8, 0
	v_mad_u64_u32 v[64:65], s[10:11], v64, s73, v[2:3]
	v_mad_u64_u32 v[66:67], s[10:11], v66, s73, v[2:3]
	v_mad_u64_u32 v[68:69], s[10:11], v68, s73, v[2:3]
	v_mad_u64_u32 v[70:71], s[10:11], v70, s73, v[2:3]
	v_mad_u64_u32 v[72:73], s[10:11], v72, s73, v[2:3]
	v_mad_u64_u32 v[74:75], s[10:11], v74, s73, v[2:3]
	v_mad_u64_u32 v[76:77], s[10:11], v76, s73, v[2:3]
	v_mad_u64_u32 v[78:79], s[10:11], v78, s73, v[2:3]
	v_mad_u64_u32 v[82:83], s[10:11], v82, s73, v[2:3]
	v_mad_u64_u32 v[84:85], s[10:11], v84, s73, v[2:3]
	v_mad_u64_u32 v[86:87], s[10:11], v86, s73, v[2:3]
	v_mad_u64_u32 v[88:89], s[10:11], v88, s73, v[2:3]
	v_mad_u64_u32 v[90:91], s[10:11], v90, s73, v[2:3]
	v_mad_u64_u32 v[92:93], s[10:11], v92, s73, v[2:3]
	v_mad_u64_u32 v[94:95], s[10:11], v94, s73, v[2:3]
	v_mad_u64_u32 v[96:97], s[10:11], v96, s73, v[2:3]
	s_waitcnt vmcnt(0)
	ds_write_b32 v64, v80
	ds_write_b32 v66, v98
	ds_write_b32 v68, v99
	ds_write_b32 v70, v100
	ds_write_b32 v72, v101
	ds_write_b32 v74, v102
	ds_write_b32 v76, v103
	ds_write_b32 v78, v104
	ds_write_b32 v82, v105
	ds_write_b32 v84, v106
	ds_write_b32 v86, v107
	ds_write_b32 v88, v108
	ds_write_b32 v90, v109
	ds_write_b32 v92, v110
	ds_write_b32 v94, v111
	ds_write_b32 v96, v112
	s_cbranch_scc1 .LBB0_548
	s_waitcnt lgkmcnt(0)
	v_add_u32_e32 v48, s0, v59
	ds_read2_b32 v[42:43], v60 offset1:33
	s_lshl_b32 s18, s1, 1
	v_ashrrev_i32_e32 v49, 31, v48
	s_waitcnt lgkmcnt(0)
	v_cvt_pk_bf16_f32 v42, v42, v43
	ds_read2_b32 v[44:45], v60 offset0:66 offset1:99
	v_lshl_add_u64 v[50:51], v[4:5], 0, s[18:19]
	v_lshlrev_b64 v[48:49], 13, v[48:49]
	s_waitcnt lgkmcnt(0)
	v_cvt_pk_bf16_f32 v43, v44, v45
	ds_read2_b32 v[44:45], v60 offset0:132 offset1:165
	v_lshl_add_u64 v[48:49], v[50:51], 0, v[48:49]
	s_waitcnt lgkmcnt(0)
	v_cvt_pk_bf16_f32 v44, v44, v45
	ds_read2_b32 v[46:47], v60 offset0:198 offset1:231
	s_waitcnt lgkmcnt(0)
	v_cvt_pk_bf16_f32 v45, v46, v47
	global_store_dwordx4 v[48:49], v[42:45], off
	v_add_u32_e32 v48, s0, v61
	v_ashrrev_i32_e32 v49, 31, v48
	ds_read2_b32 v[46:47], v60 offset0:8 offset1:41
	s_waitcnt lgkmcnt(0)
	v_cvt_pk_bf16_f32 v42, v46, v47
	ds_read2_b32 v[44:45], v60 offset0:74 offset1:107
	v_lshlrev_b64 v[48:49], 13, v[48:49]
	s_waitcnt lgkmcnt(0)
	v_cvt_pk_bf16_f32 v43, v44, v45
	ds_read2_b32 v[44:45], v60 offset0:140 offset1:173
	v_lshl_add_u64 v[48:49], v[50:51], 0, v[48:49]
	s_waitcnt lgkmcnt(0)
	v_cvt_pk_bf16_f32 v44, v44, v45
	ds_read2_b32 v[46:47], v60 offset0:206 offset1:239
	s_waitcnt lgkmcnt(0)
	v_cvt_pk_bf16_f32 v45, v46, v47
	global_store_dwordx4 v[48:49], v[42:45], off
	v_add_u32_e32 v48, s0, v62
	ds_read2_b32 v[46:47], v60 offset0:16 offset1:49
	s_waitcnt lgkmcnt(0)
	v_cvt_pk_bf16_f32 v42, v46, v47
	ds_read2_b32 v[44:45], v60 offset0:82 offset1:115
	v_ashrrev_i32_e32 v49, 31, v48
	s_waitcnt lgkmcnt(0)
	v_cvt_pk_bf16_f32 v43, v44, v45
	ds_read2_b32 v[44:45], v60 offset0:148 offset1:181
	v_lshlrev_b64 v[48:49], 13, v[48:49]
	s_waitcnt lgkmcnt(0)
	v_cvt_pk_bf16_f32 v44, v44, v45
	ds_read2_b32 v[46:47], v60 offset0:214 offset1:247
	s_waitcnt lgkmcnt(0)
	v_cvt_pk_bf16_f32 v45, v46, v47
	v_lshl_add_u64 v[48:49], v[50:51], 0, v[48:49]
	ds_read2_b32 v[46:47], v60 offset0:24 offset1:57
	global_store_dwordx4 v[48:49], v[42:45], off
	v_add_u32_e32 v48, s0, v63
	v_ashrrev_i32_e32 v49, 31, v48
	s_waitcnt lgkmcnt(0)
	v_cvt_pk_bf16_f32 v42, v46, v47
	ds_read2_b32 v[44:45], v60 offset0:90 offset1:123
	s_waitcnt lgkmcnt(0)
	v_cvt_pk_bf16_f32 v43, v44, v45
	ds_read2_b32 v[44:45], v60 offset0:156 offset1:189
	s_waitcnt lgkmcnt(0)
	v_cvt_pk_bf16_f32 v44, v44, v45
	ds_read2_b32 v[46:47], v60 offset0:222 offset1:255
	v_lshlrev_b64 v[48:49], 13, v[48:49]
	s_waitcnt lgkmcnt(0)
	v_cvt_pk_bf16_f32 v45, v46, v47
	v_lshl_add_u64 v[46:47], v[50:51], 0, v[48:49]
	global_store_dwordx4 v[46:47], v[42:45], off
	s_waitcnt lgkmcnt(0)
	s_mov_b64 s[0:1], 0

.LBB0_552:
	s_lshl_b32 s9, s5, 1
	s_lshl_b32 s10, s4, 1
	v_add_u32_e32 v66, s9, v44
	v_add_u32_e32 v64, s10, v41
	v_add_u32_e32 v68, s10, v45
	v_add_u32_e32 v70, s9, v46
	v_add_u32_e32 v72, s10, v47
	v_add_u32_e32 v74, s9, v48
	v_add_u32_e32 v76, s10, v49
	v_add_u32_e32 v78, s9, v50
	v_add_u32_e32 v82, s10, v51
	v_add_u32_e32 v84, s9, v52
	v_add_u32_e32 v86, s10, v53
	v_add_u32_e32 v88, s9, v54
	v_add_u32_e32 v90, s10, v55
	v_add_u32_e32 v92, s9, v56
	v_add_u32_e32 v94, s10, v57
	v_add_u32_e32 v96, s9, v58
	v_ashrrev_i32_e32 v67, 31, v66
	v_ashrrev_i32_e32 v65, 31, v64
	v_ashrrev_i32_e32 v71, 31, v70
	v_ashrrev_i32_e32 v69, 31, v68
	v_ashrrev_i32_e32 v75, 31, v74
	v_ashrrev_i32_e32 v73, 31, v72
	v_ashrrev_i32_e32 v79, 31, v78
	v_ashrrev_i32_e32 v77, 31, v76
	v_ashrrev_i32_e32 v85, 31, v84
	v_ashrrev_i32_e32 v83, 31, v82
	v_ashrrev_i32_e32 v89, 31, v88
	v_ashrrev_i32_e32 v87, 31, v86
	v_ashrrev_i32_e32 v93, 31, v92
	v_ashrrev_i32_e32 v91, 31, v90
	v_ashrrev_i32_e32 v97, 31, v96
	v_ashrrev_i32_e32 v95, 31, v94
	v_lshlrev_b64 v[66:67], 14, v[66:67]
	v_lshlrev_b64 v[64:65], 14, v[64:65]
	v_lshlrev_b64 v[68:69], 14, v[68:69]
	v_lshlrev_b64 v[70:71], 14, v[70:71]
	v_lshlrev_b64 v[72:73], 14, v[72:73]
	v_lshlrev_b64 v[74:75], 14, v[74:75]
	v_lshlrev_b64 v[76:77], 14, v[76:77]
	v_lshlrev_b64 v[78:79], 14, v[78:79]
	v_lshlrev_b64 v[82:83], 14, v[82:83]
	v_lshlrev_b64 v[84:85], 14, v[84:85]
	v_lshlrev_b64 v[86:87], 14, v[86:87]
	v_lshlrev_b64 v[88:89], 14, v[88:89]
	v_lshlrev_b64 v[90:91], 14, v[90:91]
	v_lshlrev_b64 v[92:93], 14, v[92:93]
	v_lshlrev_b64 v[94:95], 14, v[94:95]
	v_lshlrev_b64 v[96:97], 14, v[96:97]
	v_lshl_add_u64 v[66:67], v[42:43], 0, v[66:67]
	v_lshl_add_u64 v[64:65], v[42:43], 0, v[64:65]
	v_lshl_add_u64 v[70:71], v[42:43], 0, v[70:71]
	v_lshl_add_u64 v[68:69], v[42:43], 0, v[68:69]
	v_lshl_add_u64 v[74:75], v[42:43], 0, v[74:75]
	v_lshl_add_u64 v[72:73], v[42:43], 0, v[72:73]
	v_lshl_add_u64 v[78:79], v[42:43], 0, v[78:79]
	v_lshl_add_u64 v[76:77], v[42:43], 0, v[76:77]
	v_lshl_add_u64 v[84:85], v[42:43], 0, v[84:85]
	v_lshl_add_u64 v[82:83], v[42:43], 0, v[82:83]
	v_lshl_add_u64 v[88:89], v[42:43], 0, v[88:89]
	v_lshl_add_u64 v[86:87], v[42:43], 0, v[86:87]
	v_lshl_add_u64 v[92:93], v[42:43], 0, v[92:93]
	v_lshl_add_u64 v[90:91], v[42:43], 0, v[90:91]
	v_lshl_add_u64 v[96:97], v[42:43], 0, v[96:97]
	v_lshl_add_u64 v[94:95], v[42:43], 0, v[94:95]
	global_load_dword v80, v[66:67], off nt
	global_load_dword v98, v[64:65], off nt
	global_load_dword v99, v[70:71], off nt
	global_load_dword v100, v[68:69], off nt
	global_load_dword v101, v[74:75], off nt
	global_load_dword v102, v[72:73], off nt
	global_load_dword v103, v[78:79], off nt
	global_load_dword v104, v[76:77], off nt
	global_load_dword v105, v[84:85], off nt
	global_load_dword v106, v[82:83], off nt
	global_load_dword v107, v[88:89], off nt
	global_load_dword v108, v[86:87], off nt
	global_load_dword v109, v[92:93], off nt
	global_load_dword v110, v[90:91], off nt
	global_load_dword v111, v[96:97], off nt
	global_load_dword v112, v[94:95], off nt
	s_add_i32 s5, s5, 16
	s_add_i32 s4, s4, 16
	s_add_i32 s8, s8, -16
	v_add_u32_e32 v64, s9, v0
	v_add_u32_e32 v66, s10, v1
	v_add_u32_e32 v70, s10, v3
	v_add_u32_e32 v68, s9, v28
	v_add_u32_e32 v74, s10, v29
	v_add_u32_e32 v72, s9, v30
	v_add_u32_e32 v78, s10, v31
	v_add_u32_e32 v76, s9, v32
	v_add_u32_e32 v84, s10, v33
	v_add_u32_e32 v82, s9, v34
	v_add_u32_e32 v88, s10, v35
	v_add_u32_e32 v86, s9, v36
	v_add_u32_e32 v92, s10, v37
	v_add_u32_e32 v90, s9, v38
	v_add_u32_e32 v96, s10, v39
	v_add_u32_e32 v94, s9, v40
	s_cmp_lg_u32 s8, 0
	v_mad_u64_u32 v[64:65], s[10:11], v64, s73, v[2:3]
	v_mad_u64_u32 v[66:67], s[10:11], v66, s73, v[2:3]
	v_mad_u64_u32 v[68:69], s[10:11], v68, s73, v[2:3]
	v_mad_u64_u32 v[70:71], s[10:11], v70, s73, v[2:3]
	v_mad_u64_u32 v[72:73], s[10:11], v72, s73, v[2:3]
	v_mad_u64_u32 v[74:75], s[10:11], v74, s73, v[2:3]
	v_mad_u64_u32 v[76:77], s[10:11], v76, s73, v[2:3]
	v_mad_u64_u32 v[78:79], s[10:11], v78, s73, v[2:3]
	v_mad_u64_u32 v[82:83], s[10:11], v82, s73, v[2:3]
	v_mad_u64_u32 v[84:85], s[10:11], v84, s73, v[2:3]
	v_mad_u64_u32 v[86:87], s[10:11], v86, s73, v[2:3]
	v_mad_u64_u32 v[88:89], s[10:11], v88, s73, v[2:3]
	v_mad_u64_u32 v[90:91], s[10:11], v90, s73, v[2:3]
	v_mad_u64_u32 v[92:93], s[10:11], v92, s73, v[2:3]
	v_mad_u64_u32 v[94:95], s[10:11], v94, s73, v[2:3]
	v_mad_u64_u32 v[96:97], s[10:11], v96, s73, v[2:3]
	s_waitcnt vmcnt(0)
	ds_write_b32 v64, v80
	ds_write_b32 v66, v98
	ds_write_b32 v68, v99
	ds_write_b32 v70, v100
	ds_write_b32 v72, v101
	ds_write_b32 v74, v102
	ds_write_b32 v76, v103
	ds_write_b32 v78, v104
	ds_write_b32 v82, v105
	ds_write_b32 v84, v106
	ds_write_b32 v86, v107
	ds_write_b32 v88, v108
	ds_write_b32 v90, v109
	ds_write_b32 v92, v110
	ds_write_b32 v94, v111
	ds_write_b32 v96, v112
	s_cbranch_scc1 .LBB0_552
	s_waitcnt lgkmcnt(0)
	v_add_u32_e32 v48, s0, v59
	ds_read2_b32 v[42:43], v60 offset1:33
	s_lshl_b32 s18, s1, 1
	v_ashrrev_i32_e32 v49, 31, v48
	s_waitcnt lgkmcnt(0)
	v_cvt_pk_bf16_f32 v42, v42, v43
	ds_read2_b32 v[44:45], v60 offset0:66 offset1:99
	v_lshl_add_u64 v[50:51], v[6:7], 0, s[18:19]
	v_lshlrev_b64 v[48:49], 11, v[48:49]
	s_waitcnt lgkmcnt(0)
	v_cvt_pk_bf16_f32 v43, v44, v45
	ds_read2_b32 v[44:45], v60 offset0:132 offset1:165
	v_lshl_add_u64 v[48:49], v[50:51], 0, v[48:49]
	s_waitcnt lgkmcnt(0)
	v_cvt_pk_bf16_f32 v44, v44, v45
	ds_read2_b32 v[46:47], v60 offset0:198 offset1:231
	s_waitcnt lgkmcnt(0)
	v_cvt_pk_bf16_f32 v45, v46, v47
	global_store_dwordx4 v[48:49], v[42:45], off
	v_add_u32_e32 v48, s0, v61
	v_ashrrev_i32_e32 v49, 31, v48
	ds_read2_b32 v[46:47], v60 offset0:8 offset1:41
	s_waitcnt lgkmcnt(0)
	v_cvt_pk_bf16_f32 v42, v46, v47
	ds_read2_b32 v[44:45], v60 offset0:74 offset1:107
	v_lshlrev_b64 v[48:49], 11, v[48:49]
	s_waitcnt lgkmcnt(0)
	v_cvt_pk_bf16_f32 v43, v44, v45
	ds_read2_b32 v[44:45], v60 offset0:140 offset1:173
	v_lshl_add_u64 v[48:49], v[50:51], 0, v[48:49]
	s_waitcnt lgkmcnt(0)
	v_cvt_pk_bf16_f32 v44, v44, v45
	ds_read2_b32 v[46:47], v60 offset0:206 offset1:239
	s_waitcnt lgkmcnt(0)
	v_cvt_pk_bf16_f32 v45, v46, v47
	global_store_dwordx4 v[48:49], v[42:45], off
	v_add_u32_e32 v48, s0, v62
	ds_read2_b32 v[46:47], v60 offset0:16 offset1:49
	s_waitcnt lgkmcnt(0)
	v_cvt_pk_bf16_f32 v42, v46, v47
	ds_read2_b32 v[44:45], v60 offset0:82 offset1:115
	v_ashrrev_i32_e32 v49, 31, v48
	s_waitcnt lgkmcnt(0)
	v_cvt_pk_bf16_f32 v43, v44, v45
	ds_read2_b32 v[44:45], v60 offset0:148 offset1:181
	v_lshlrev_b64 v[48:49], 11, v[48:49]
	s_waitcnt lgkmcnt(0)
	v_cvt_pk_bf16_f32 v44, v44, v45
	ds_read2_b32 v[46:47], v60 offset0:214 offset1:247
	s_waitcnt lgkmcnt(0)
	v_cvt_pk_bf16_f32 v45, v46, v47
	v_lshl_add_u64 v[48:49], v[50:51], 0, v[48:49]
	ds_read2_b32 v[46:47], v60 offset0:24 offset1:57
	global_store_dwordx4 v[48:49], v[42:45], off
	v_add_u32_e32 v48, s0, v63
	v_ashrrev_i32_e32 v49, 31, v48
	s_waitcnt lgkmcnt(0)
	v_cvt_pk_bf16_f32 v42, v46, v47
	ds_read2_b32 v[44:45], v60 offset0:90 offset1:123
	s_waitcnt lgkmcnt(0)
	v_cvt_pk_bf16_f32 v43, v44, v45
	ds_read2_b32 v[44:45], v60 offset0:156 offset1:189
	s_waitcnt lgkmcnt(0)
	v_cvt_pk_bf16_f32 v44, v44, v45
	ds_read2_b32 v[46:47], v60 offset0:222 offset1:255
	v_lshlrev_b64 v[48:49], 11, v[48:49]
	s_waitcnt lgkmcnt(0)
	v_cvt_pk_bf16_f32 v45, v46, v47
	v_lshl_add_u64 v[46:47], v[50:51], 0, v[48:49]
	global_store_dwordx4 v[46:47], v[42:45], off
	s_waitcnt lgkmcnt(0)

.LBB0_557:
	s_lshl_b32 s9, s5, 1
	s_lshl_b32 s10, s4, 1
	v_add_u32_e32 v66, s9, v44
	v_add_u32_e32 v64, s10, v41
	v_add_u32_e32 v68, s10, v45
	v_add_u32_e32 v70, s9, v46
	v_add_u32_e32 v72, s10, v47
	v_add_u32_e32 v74, s9, v48
	v_add_u32_e32 v76, s10, v49
	v_add_u32_e32 v78, s9, v50
	v_add_u32_e32 v82, s10, v51
	v_add_u32_e32 v84, s9, v52
	v_add_u32_e32 v86, s10, v53
	v_add_u32_e32 v88, s9, v54
	v_add_u32_e32 v90, s10, v55
	v_add_u32_e32 v92, s9, v56
	v_add_u32_e32 v94, s10, v57
	v_add_u32_e32 v96, s9, v58
	v_ashrrev_i32_e32 v67, 31, v66
	v_ashrrev_i32_e32 v65, 31, v64
	v_ashrrev_i32_e32 v71, 31, v70
	v_ashrrev_i32_e32 v69, 31, v68
	v_ashrrev_i32_e32 v75, 31, v74
	v_ashrrev_i32_e32 v73, 31, v72
	v_ashrrev_i32_e32 v79, 31, v78
	v_ashrrev_i32_e32 v77, 31, v76
	v_ashrrev_i32_e32 v85, 31, v84
	v_ashrrev_i32_e32 v83, 31, v82
	v_ashrrev_i32_e32 v89, 31, v88
	v_ashrrev_i32_e32 v87, 31, v86
	v_ashrrev_i32_e32 v93, 31, v92
	v_ashrrev_i32_e32 v91, 31, v90
	v_ashrrev_i32_e32 v97, 31, v96
	v_ashrrev_i32_e32 v95, 31, v94
	v_lshlrev_b64 v[66:67], 12, v[66:67]
	v_lshlrev_b64 v[64:65], 12, v[64:65]
	v_lshlrev_b64 v[68:69], 12, v[68:69]
	v_lshlrev_b64 v[70:71], 12, v[70:71]
	v_lshlrev_b64 v[72:73], 12, v[72:73]
	v_lshlrev_b64 v[74:75], 12, v[74:75]
	v_lshlrev_b64 v[76:77], 12, v[76:77]
	v_lshlrev_b64 v[78:79], 12, v[78:79]
	v_lshlrev_b64 v[82:83], 12, v[82:83]
	v_lshlrev_b64 v[84:85], 12, v[84:85]
	v_lshlrev_b64 v[86:87], 12, v[86:87]
	v_lshlrev_b64 v[88:89], 12, v[88:89]
	v_lshlrev_b64 v[90:91], 12, v[90:91]
	v_lshlrev_b64 v[92:93], 12, v[92:93]
	v_lshlrev_b64 v[94:95], 12, v[94:95]
	v_lshlrev_b64 v[96:97], 12, v[96:97]
	v_lshl_add_u64 v[66:67], v[42:43], 0, v[66:67]
	v_lshl_add_u64 v[64:65], v[42:43], 0, v[64:65]
	v_lshl_add_u64 v[70:71], v[42:43], 0, v[70:71]
	v_lshl_add_u64 v[68:69], v[42:43], 0, v[68:69]
	v_lshl_add_u64 v[74:75], v[42:43], 0, v[74:75]
	v_lshl_add_u64 v[72:73], v[42:43], 0, v[72:73]
	v_lshl_add_u64 v[78:79], v[42:43], 0, v[78:79]
	v_lshl_add_u64 v[76:77], v[42:43], 0, v[76:77]
	v_lshl_add_u64 v[84:85], v[42:43], 0, v[84:85]
	v_lshl_add_u64 v[82:83], v[42:43], 0, v[82:83]
	v_lshl_add_u64 v[88:89], v[42:43], 0, v[88:89]
	v_lshl_add_u64 v[86:87], v[42:43], 0, v[86:87]
	v_lshl_add_u64 v[92:93], v[42:43], 0, v[92:93]
	v_lshl_add_u64 v[90:91], v[42:43], 0, v[90:91]
	v_lshl_add_u64 v[96:97], v[42:43], 0, v[96:97]
	v_lshl_add_u64 v[94:95], v[42:43], 0, v[94:95]
	global_load_dword v80, v[66:67], off nt
	global_load_dword v98, v[64:65], off nt
	global_load_dword v99, v[70:71], off nt
	global_load_dword v100, v[68:69], off nt
	global_load_dword v101, v[74:75], off nt
	global_load_dword v102, v[72:73], off nt
	global_load_dword v103, v[78:79], off nt
	global_load_dword v104, v[76:77], off nt
	global_load_dword v105, v[84:85], off nt
	global_load_dword v106, v[82:83], off nt
	global_load_dword v107, v[88:89], off nt
	global_load_dword v108, v[86:87], off nt
	global_load_dword v109, v[92:93], off nt
	global_load_dword v110, v[90:91], off nt
	global_load_dword v111, v[96:97], off nt
	global_load_dword v112, v[94:95], off nt
	s_add_i32 s5, s5, 16
	s_add_i32 s4, s4, 16
	s_add_i32 s8, s8, -16
	v_add_u32_e32 v64, s9, v0
	v_add_u32_e32 v66, s10, v1
	v_add_u32_e32 v70, s10, v3
	v_add_u32_e32 v68, s9, v28
	v_add_u32_e32 v74, s10, v29
	v_add_u32_e32 v72, s9, v30
	v_add_u32_e32 v78, s10, v31
	v_add_u32_e32 v76, s9, v32
	v_add_u32_e32 v84, s10, v33
	v_add_u32_e32 v82, s9, v34
	v_add_u32_e32 v88, s10, v35
	v_add_u32_e32 v86, s9, v36
	v_add_u32_e32 v92, s10, v37
	v_add_u32_e32 v90, s9, v38
	v_add_u32_e32 v96, s10, v39
	v_add_u32_e32 v94, s9, v40
	s_cmp_lg_u32 s8, 0
	v_mad_u64_u32 v[64:65], s[10:11], v64, s73, v[2:3]
	v_mad_u64_u32 v[66:67], s[10:11], v66, s73, v[2:3]
	v_mad_u64_u32 v[68:69], s[10:11], v68, s73, v[2:3]
	v_mad_u64_u32 v[70:71], s[10:11], v70, s73, v[2:3]
	v_mad_u64_u32 v[72:73], s[10:11], v72, s73, v[2:3]
	v_mad_u64_u32 v[74:75], s[10:11], v74, s73, v[2:3]
	v_mad_u64_u32 v[76:77], s[10:11], v76, s73, v[2:3]
	v_mad_u64_u32 v[78:79], s[10:11], v78, s73, v[2:3]
	v_mad_u64_u32 v[82:83], s[10:11], v82, s73, v[2:3]
	v_mad_u64_u32 v[84:85], s[10:11], v84, s73, v[2:3]
	v_mad_u64_u32 v[86:87], s[10:11], v86, s73, v[2:3]
	v_mad_u64_u32 v[88:89], s[10:11], v88, s73, v[2:3]
	v_mad_u64_u32 v[90:91], s[10:11], v90, s73, v[2:3]
	v_mad_u64_u32 v[92:93], s[10:11], v92, s73, v[2:3]
	v_mad_u64_u32 v[94:95], s[10:11], v94, s73, v[2:3]
	v_mad_u64_u32 v[96:97], s[10:11], v96, s73, v[2:3]
	s_waitcnt vmcnt(0)
	ds_write_b32 v64, v80
	ds_write_b32 v66, v98
	ds_write_b32 v68, v99
	ds_write_b32 v70, v100
	ds_write_b32 v72, v101
	ds_write_b32 v74, v102
	ds_write_b32 v76, v103
	ds_write_b32 v78, v104
	ds_write_b32 v82, v105
	ds_write_b32 v84, v106
	ds_write_b32 v86, v107
	ds_write_b32 v88, v108
	ds_write_b32 v90, v109
	ds_write_b32 v92, v110
	ds_write_b32 v94, v111
	ds_write_b32 v96, v112
	s_cbranch_scc1 .LBB0_557
	s_waitcnt lgkmcnt(0)
	v_add_u32_e32 v48, s0, v59
	ds_read2_b32 v[42:43], v60 offset1:33
	s_lshl_b32 s18, s1, 1
	v_ashrrev_i32_e32 v49, 31, v48
	s_waitcnt lgkmcnt(0)
	v_cvt_pk_bf16_f32 v42, v42, v43
	ds_read2_b32 v[44:45], v60 offset0:66 offset1:99
	v_lshl_add_u64 v[50:51], v[8:9], 0, s[18:19]
	v_lshlrev_b64 v[48:49], 11, v[48:49]
	s_waitcnt lgkmcnt(0)
	v_cvt_pk_bf16_f32 v43, v44, v45
	ds_read2_b32 v[44:45], v60 offset0:132 offset1:165
	v_lshl_add_u64 v[48:49], v[50:51], 0, v[48:49]
	s_waitcnt lgkmcnt(0)
	v_cvt_pk_bf16_f32 v44, v44, v45
	ds_read2_b32 v[46:47], v60 offset0:198 offset1:231
	s_waitcnt lgkmcnt(0)
	v_cvt_pk_bf16_f32 v45, v46, v47
	global_store_dwordx4 v[48:49], v[42:45], off
	v_add_u32_e32 v48, s0, v61
	v_ashrrev_i32_e32 v49, 31, v48
	ds_read2_b32 v[46:47], v60 offset0:8 offset1:41
	s_waitcnt lgkmcnt(0)
	v_cvt_pk_bf16_f32 v42, v46, v47
	ds_read2_b32 v[44:45], v60 offset0:74 offset1:107
	v_lshlrev_b64 v[48:49], 11, v[48:49]
	s_waitcnt lgkmcnt(0)
	v_cvt_pk_bf16_f32 v43, v44, v45
	ds_read2_b32 v[44:45], v60 offset0:140 offset1:173
	v_lshl_add_u64 v[48:49], v[50:51], 0, v[48:49]
	s_waitcnt lgkmcnt(0)
	v_cvt_pk_bf16_f32 v44, v44, v45
	ds_read2_b32 v[46:47], v60 offset0:206 offset1:239
	s_waitcnt lgkmcnt(0)
	v_cvt_pk_bf16_f32 v45, v46, v47
	global_store_dwordx4 v[48:49], v[42:45], off
	v_add_u32_e32 v48, s0, v62
	ds_read2_b32 v[46:47], v60 offset0:16 offset1:49
	s_waitcnt lgkmcnt(0)
	v_cvt_pk_bf16_f32 v42, v46, v47
	ds_read2_b32 v[44:45], v60 offset0:82 offset1:115
	v_ashrrev_i32_e32 v49, 31, v48
	s_waitcnt lgkmcnt(0)
	v_cvt_pk_bf16_f32 v43, v44, v45
	ds_read2_b32 v[44:45], v60 offset0:148 offset1:181
	v_lshlrev_b64 v[48:49], 11, v[48:49]
	s_waitcnt lgkmcnt(0)
	v_cvt_pk_bf16_f32 v44, v44, v45
	ds_read2_b32 v[46:47], v60 offset0:214 offset1:247
	s_waitcnt lgkmcnt(0)
	v_cvt_pk_bf16_f32 v45, v46, v47
	v_lshl_add_u64 v[48:49], v[50:51], 0, v[48:49]
	ds_read2_b32 v[46:47], v60 offset0:24 offset1:57
	global_store_dwordx4 v[48:49], v[42:45], off
	v_add_u32_e32 v48, s0, v63
	v_ashrrev_i32_e32 v49, 31, v48
	s_waitcnt lgkmcnt(0)
	v_cvt_pk_bf16_f32 v42, v46, v47
	ds_read2_b32 v[44:45], v60 offset0:90 offset1:123
	s_waitcnt lgkmcnt(0)
	v_cvt_pk_bf16_f32 v43, v44, v45
	ds_read2_b32 v[44:45], v60 offset0:156 offset1:189
	s_waitcnt lgkmcnt(0)
	v_cvt_pk_bf16_f32 v44, v44, v45
	ds_read2_b32 v[46:47], v60 offset0:222 offset1:255
	v_lshlrev_b64 v[48:49], 11, v[48:49]
	s_waitcnt lgkmcnt(0)
	v_cvt_pk_bf16_f32 v45, v46, v47
	v_lshl_add_u64 v[46:47], v[50:51], 0, v[48:49]
	global_store_dwordx4 v[46:47], v[42:45], off
	s_waitcnt lgkmcnt(0)

.LBB0_562:
	s_lshl_b32 s9, s5, 1
	s_lshl_b32 s10, s4, 1
	v_add_u32_e32 v66, s9, v44
	v_add_u32_e32 v64, s10, v41
	v_add_u32_e32 v68, s10, v45
	v_add_u32_e32 v70, s9, v46
	v_add_u32_e32 v72, s10, v47
	v_add_u32_e32 v74, s9, v48
	v_add_u32_e32 v76, s10, v49
	v_add_u32_e32 v78, s9, v50
	v_add_u32_e32 v82, s10, v51
	v_add_u32_e32 v84, s9, v52
	v_add_u32_e32 v86, s10, v53
	v_add_u32_e32 v88, s9, v54
	v_add_u32_e32 v90, s10, v55
	v_add_u32_e32 v92, s9, v56
	v_add_u32_e32 v94, s10, v57
	v_add_u32_e32 v96, s9, v58
	v_ashrrev_i32_e32 v67, 31, v66
	v_ashrrev_i32_e32 v65, 31, v64
	v_ashrrev_i32_e32 v71, 31, v70
	v_ashrrev_i32_e32 v69, 31, v68
	v_ashrrev_i32_e32 v75, 31, v74
	v_ashrrev_i32_e32 v73, 31, v72
	v_ashrrev_i32_e32 v79, 31, v78
	v_ashrrev_i32_e32 v77, 31, v76
	v_ashrrev_i32_e32 v85, 31, v84
	v_ashrrev_i32_e32 v83, 31, v82
	v_ashrrev_i32_e32 v89, 31, v88
	v_ashrrev_i32_e32 v87, 31, v86
	v_ashrrev_i32_e32 v93, 31, v92
	v_ashrrev_i32_e32 v91, 31, v90
	v_ashrrev_i32_e32 v97, 31, v96
	v_ashrrev_i32_e32 v95, 31, v94
	v_lshlrev_b64 v[66:67], 12, v[66:67]
	v_lshlrev_b64 v[64:65], 12, v[64:65]
	v_lshlrev_b64 v[68:69], 12, v[68:69]
	v_lshlrev_b64 v[70:71], 12, v[70:71]
	v_lshlrev_b64 v[72:73], 12, v[72:73]
	v_lshlrev_b64 v[74:75], 12, v[74:75]
	v_lshlrev_b64 v[76:77], 12, v[76:77]
	v_lshlrev_b64 v[78:79], 12, v[78:79]
	v_lshlrev_b64 v[82:83], 12, v[82:83]
	v_lshlrev_b64 v[84:85], 12, v[84:85]
	v_lshlrev_b64 v[86:87], 12, v[86:87]
	v_lshlrev_b64 v[88:89], 12, v[88:89]
	v_lshlrev_b64 v[90:91], 12, v[90:91]
	v_lshlrev_b64 v[92:93], 12, v[92:93]
	v_lshlrev_b64 v[94:95], 12, v[94:95]
	v_lshlrev_b64 v[96:97], 12, v[96:97]
	v_lshl_add_u64 v[66:67], v[42:43], 0, v[66:67]
	v_lshl_add_u64 v[64:65], v[42:43], 0, v[64:65]
	v_lshl_add_u64 v[70:71], v[42:43], 0, v[70:71]
	v_lshl_add_u64 v[68:69], v[42:43], 0, v[68:69]
	v_lshl_add_u64 v[74:75], v[42:43], 0, v[74:75]
	v_lshl_add_u64 v[72:73], v[42:43], 0, v[72:73]
	v_lshl_add_u64 v[78:79], v[42:43], 0, v[78:79]
	v_lshl_add_u64 v[76:77], v[42:43], 0, v[76:77]
	v_lshl_add_u64 v[84:85], v[42:43], 0, v[84:85]
	v_lshl_add_u64 v[82:83], v[42:43], 0, v[82:83]
	v_lshl_add_u64 v[88:89], v[42:43], 0, v[88:89]
	v_lshl_add_u64 v[86:87], v[42:43], 0, v[86:87]
	v_lshl_add_u64 v[92:93], v[42:43], 0, v[92:93]
	v_lshl_add_u64 v[90:91], v[42:43], 0, v[90:91]
	v_lshl_add_u64 v[96:97], v[42:43], 0, v[96:97]
	v_lshl_add_u64 v[94:95], v[42:43], 0, v[94:95]
	global_load_dword v80, v[66:67], off nt
	global_load_dword v98, v[64:65], off nt
	global_load_dword v99, v[70:71], off nt
	global_load_dword v100, v[68:69], off nt
	global_load_dword v101, v[74:75], off nt
	global_load_dword v102, v[72:73], off nt
	global_load_dword v103, v[78:79], off nt
	global_load_dword v104, v[76:77], off nt
	global_load_dword v105, v[84:85], off nt
	global_load_dword v106, v[82:83], off nt
	global_load_dword v107, v[88:89], off nt
	global_load_dword v108, v[86:87], off nt
	global_load_dword v109, v[92:93], off nt
	global_load_dword v110, v[90:91], off nt
	global_load_dword v111, v[96:97], off nt
	global_load_dword v112, v[94:95], off nt
	s_add_i32 s5, s5, 16
	s_add_i32 s4, s4, 16
	s_add_i32 s8, s8, -16
	v_add_u32_e32 v64, s9, v0
	v_add_u32_e32 v66, s10, v1
	v_add_u32_e32 v70, s10, v3
	v_add_u32_e32 v68, s9, v28
	v_add_u32_e32 v74, s10, v29
	v_add_u32_e32 v72, s9, v30
	v_add_u32_e32 v78, s10, v31
	v_add_u32_e32 v76, s9, v32
	v_add_u32_e32 v84, s10, v33
	v_add_u32_e32 v82, s9, v34
	v_add_u32_e32 v88, s10, v35
	v_add_u32_e32 v86, s9, v36
	v_add_u32_e32 v92, s10, v37
	v_add_u32_e32 v90, s9, v38
	v_add_u32_e32 v96, s10, v39
	v_add_u32_e32 v94, s9, v40
	s_cmp_lg_u32 s8, 0
	v_mad_u64_u32 v[64:65], s[10:11], v64, s73, v[2:3]
	v_mad_u64_u32 v[66:67], s[10:11], v66, s73, v[2:3]
	v_mad_u64_u32 v[68:69], s[10:11], v68, s73, v[2:3]
	v_mad_u64_u32 v[70:71], s[10:11], v70, s73, v[2:3]
	v_mad_u64_u32 v[72:73], s[10:11], v72, s73, v[2:3]
	v_mad_u64_u32 v[74:75], s[10:11], v74, s73, v[2:3]
	v_mad_u64_u32 v[76:77], s[10:11], v76, s73, v[2:3]
	v_mad_u64_u32 v[78:79], s[10:11], v78, s73, v[2:3]
	v_mad_u64_u32 v[82:83], s[10:11], v82, s73, v[2:3]
	v_mad_u64_u32 v[84:85], s[10:11], v84, s73, v[2:3]
	v_mad_u64_u32 v[86:87], s[10:11], v86, s73, v[2:3]
	v_mad_u64_u32 v[88:89], s[10:11], v88, s73, v[2:3]
	v_mad_u64_u32 v[90:91], s[10:11], v90, s73, v[2:3]
	v_mad_u64_u32 v[92:93], s[10:11], v92, s73, v[2:3]
	v_mad_u64_u32 v[94:95], s[10:11], v94, s73, v[2:3]
	v_mad_u64_u32 v[96:97], s[10:11], v96, s73, v[2:3]
	s_waitcnt vmcnt(0)
	ds_write_b32 v64, v80
	ds_write_b32 v66, v98
	ds_write_b32 v68, v99
	ds_write_b32 v70, v100
	ds_write_b32 v72, v101
	ds_write_b32 v74, v102
	ds_write_b32 v76, v103
	ds_write_b32 v78, v104
	ds_write_b32 v82, v105
	ds_write_b32 v84, v106
	ds_write_b32 v86, v107
	ds_write_b32 v88, v108
	ds_write_b32 v90, v109
	ds_write_b32 v92, v110
	ds_write_b32 v94, v111
	ds_write_b32 v96, v112
	s_cbranch_scc1 .LBB0_562
	s_waitcnt lgkmcnt(0)
	v_add_u32_e32 v48, s0, v59
	ds_read2_b32 v[42:43], v60 offset1:33
	s_lshl_b32 s18, s1, 1
	v_ashrrev_i32_e32 v49, 31, v48
	s_waitcnt lgkmcnt(0)
	v_cvt_pk_bf16_f32 v42, v42, v43
	ds_read2_b32 v[44:45], v60 offset0:66 offset1:99
	v_lshl_add_u64 v[50:51], v[10:11], 0, s[18:19]
	v_lshlrev_b64 v[48:49], 9, v[48:49]
	s_waitcnt lgkmcnt(0)
	v_cvt_pk_bf16_f32 v43, v44, v45
	ds_read2_b32 v[44:45], v60 offset0:132 offset1:165
	v_lshl_add_u64 v[48:49], v[50:51], 0, v[48:49]
	s_waitcnt lgkmcnt(0)
	v_cvt_pk_bf16_f32 v44, v44, v45
	ds_read2_b32 v[46:47], v60 offset0:198 offset1:231
	s_waitcnt lgkmcnt(0)
	v_cvt_pk_bf16_f32 v45, v46, v47
	global_store_dwordx4 v[48:49], v[42:45], off
	v_add_u32_e32 v48, s0, v61
	v_ashrrev_i32_e32 v49, 31, v48
	ds_read2_b32 v[46:47], v60 offset0:8 offset1:41
	s_waitcnt lgkmcnt(0)
	v_cvt_pk_bf16_f32 v42, v46, v47
	ds_read2_b32 v[44:45], v60 offset0:74 offset1:107
	v_lshlrev_b64 v[48:49], 9, v[48:49]
	s_waitcnt lgkmcnt(0)
	v_cvt_pk_bf16_f32 v43, v44, v45
	ds_read2_b32 v[44:45], v60 offset0:140 offset1:173
	v_lshl_add_u64 v[48:49], v[50:51], 0, v[48:49]
	s_waitcnt lgkmcnt(0)
	v_cvt_pk_bf16_f32 v44, v44, v45
	ds_read2_b32 v[46:47], v60 offset0:206 offset1:239
	s_waitcnt lgkmcnt(0)
	v_cvt_pk_bf16_f32 v45, v46, v47
	global_store_dwordx4 v[48:49], v[42:45], off
	v_add_u32_e32 v48, s0, v62
	ds_read2_b32 v[46:47], v60 offset0:16 offset1:49
	s_waitcnt lgkmcnt(0)
	v_cvt_pk_bf16_f32 v42, v46, v47
	ds_read2_b32 v[44:45], v60 offset0:82 offset1:115
	v_ashrrev_i32_e32 v49, 31, v48
	s_waitcnt lgkmcnt(0)
	v_cvt_pk_bf16_f32 v43, v44, v45
	ds_read2_b32 v[44:45], v60 offset0:148 offset1:181
	v_lshlrev_b64 v[48:49], 9, v[48:49]
	s_waitcnt lgkmcnt(0)
	v_cvt_pk_bf16_f32 v44, v44, v45
	ds_read2_b32 v[46:47], v60 offset0:214 offset1:247
	s_waitcnt lgkmcnt(0)
	v_cvt_pk_bf16_f32 v45, v46, v47
	v_lshl_add_u64 v[48:49], v[50:51], 0, v[48:49]
	ds_read2_b32 v[46:47], v60 offset0:24 offset1:57
	global_store_dwordx4 v[48:49], v[42:45], off
	v_add_u32_e32 v48, s0, v63
	v_ashrrev_i32_e32 v49, 31, v48
	s_waitcnt lgkmcnt(0)
	v_cvt_pk_bf16_f32 v42, v46, v47
	ds_read2_b32 v[44:45], v60 offset0:90 offset1:123
	s_waitcnt lgkmcnt(0)
	v_cvt_pk_bf16_f32 v43, v44, v45
	ds_read2_b32 v[44:45], v60 offset0:156 offset1:189
	s_waitcnt lgkmcnt(0)
	v_cvt_pk_bf16_f32 v44, v44, v45
	ds_read2_b32 v[46:47], v60 offset0:222 offset1:255
	v_lshlrev_b64 v[48:49], 9, v[48:49]
	s_waitcnt lgkmcnt(0)
	v_cvt_pk_bf16_f32 v45, v46, v47
	v_lshl_add_u64 v[46:47], v[50:51], 0, v[48:49]
	global_store_dwordx4 v[46:47], v[42:45], off
	s_waitcnt lgkmcnt(0)

.LBB0_567:
	s_lshl_b32 s9, s8, 1
	s_lshl_b32 s14, s5, 1
	v_add_u32_e32 v64, s9, v44
	v_add_u32_e32 v66, s14, v41
	v_add_u32_e32 v70, s14, v45
	v_add_u32_e32 v68, s9, v46
	v_add_u32_e32 v74, s14, v47
	v_add_u32_e32 v72, s9, v48
	v_add_u32_e32 v78, s14, v49
	v_add_u32_e32 v76, s9, v50
	v_add_u32_e32 v80, s14, v51
	v_add_u32_e32 v82, s9, v52
	v_add_u32_e32 v88, s14, v53
	v_add_u32_e32 v86, s9, v54
	v_add_u32_e32 v92, s14, v55
	v_add_u32_e32 v90, s9, v56
	v_add_u32_e32 v96, s14, v57
	v_add_u32_e32 v94, s9, v58
	v_mad_i64_i32 v[64:65], s[10:11], v64, s28, v[42:43]
	v_mad_i64_i32 v[66:67], s[10:11], v66, s28, v[42:43]
	v_mad_i64_i32 v[68:69], s[10:11], v68, s28, v[42:43]
	v_mad_i64_i32 v[70:71], s[10:11], v70, s28, v[42:43]
	v_mad_i64_i32 v[72:73], s[10:11], v72, s28, v[42:43]
	v_mad_i64_i32 v[74:75], s[10:11], v74, s28, v[42:43]
	v_mad_i64_i32 v[76:77], s[10:11], v76, s28, v[42:43]
	v_mad_i64_i32 v[78:79], s[10:11], v78, s28, v[42:43]
	v_mad_i64_i32 v[82:83], s[10:11], v82, s28, v[42:43]
	v_mad_i64_i32 v[84:85], s[10:11], v80, s28, v[42:43]
	v_mad_i64_i32 v[86:87], s[10:11], v86, s28, v[42:43]
	v_mad_i64_i32 v[88:89], s[10:11], v88, s28, v[42:43]
	v_mad_i64_i32 v[90:91], s[10:11], v90, s28, v[42:43]
	v_mad_i64_i32 v[92:93], s[10:11], v92, s28, v[42:43]
	v_mad_i64_i32 v[94:95], s[10:11], v94, s28, v[42:43]
	v_mad_i64_i32 v[96:97], s[10:11], v96, s28, v[42:43]
	global_load_dword v80, v[64:65], off nt
	global_load_dword v98, v[66:67], off nt
	global_load_dword v99, v[68:69], off nt
	global_load_dword v100, v[70:71], off nt
	global_load_dword v101, v[72:73], off nt
	global_load_dword v102, v[74:75], off nt
	global_load_dword v103, v[76:77], off nt
	global_load_dword v104, v[78:79], off nt
	global_load_dword v105, v[82:83], off nt
	global_load_dword v106, v[84:85], off nt
	global_load_dword v107, v[86:87], off nt
	global_load_dword v108, v[88:89], off nt
	global_load_dword v109, v[90:91], off nt
	global_load_dword v110, v[92:93], off nt
	global_load_dword v111, v[94:95], off nt
	global_load_dword v112, v[96:97], off nt
	s_add_i32 s8, s8, 16
	s_add_i32 s5, s5, 16
	s_add_i32 s4, s4, -16
	v_add_u32_e32 v64, s9, v0
	v_add_u32_e32 v66, s14, v1
	v_add_u32_e32 v70, s14, v3
	v_add_u32_e32 v68, s9, v28
	v_add_u32_e32 v74, s14, v29
	v_add_u32_e32 v72, s9, v30
	v_add_u32_e32 v78, s14, v31
	v_add_u32_e32 v76, s9, v32
	v_add_u32_e32 v84, s14, v33
	v_add_u32_e32 v82, s9, v34
	v_add_u32_e32 v88, s14, v35
	v_add_u32_e32 v86, s9, v36
	v_add_u32_e32 v92, s14, v37
	v_add_u32_e32 v90, s9, v38
	v_add_u32_e32 v96, s14, v39
	v_add_u32_e32 v94, s9, v40
	s_cmp_lg_u32 s4, 0
	v_mad_u64_u32 v[64:65], s[10:11], v64, s73, v[2:3]
	v_mad_u64_u32 v[66:67], s[10:11], v66, s73, v[2:3]
	v_mad_u64_u32 v[68:69], s[10:11], v68, s73, v[2:3]
	v_mad_u64_u32 v[70:71], s[10:11], v70, s73, v[2:3]
	v_mad_u64_u32 v[72:73], s[10:11], v72, s73, v[2:3]
	v_mad_u64_u32 v[74:75], s[10:11], v74, s73, v[2:3]
	v_mad_u64_u32 v[76:77], s[10:11], v76, s73, v[2:3]
	v_mad_u64_u32 v[78:79], s[10:11], v78, s73, v[2:3]
	v_mad_u64_u32 v[82:83], s[10:11], v82, s73, v[2:3]
	v_mad_u64_u32 v[84:85], s[10:11], v84, s73, v[2:3]
	v_mad_u64_u32 v[86:87], s[10:11], v86, s73, v[2:3]
	v_mad_u64_u32 v[88:89], s[10:11], v88, s73, v[2:3]
	v_mad_u64_u32 v[90:91], s[10:11], v90, s73, v[2:3]
	v_mad_u64_u32 v[92:93], s[10:11], v92, s73, v[2:3]
	v_mad_u64_u32 v[94:95], s[10:11], v94, s73, v[2:3]
	v_mad_u64_u32 v[96:97], s[10:11], v96, s73, v[2:3]
	s_waitcnt vmcnt(0)
	ds_write_b32 v64, v80
	ds_write_b32 v66, v98
	ds_write_b32 v68, v99
	ds_write_b32 v70, v100
	ds_write_b32 v72, v101
	ds_write_b32 v74, v102
	ds_write_b32 v76, v103
	ds_write_b32 v78, v104
	ds_write_b32 v82, v105
	ds_write_b32 v84, v106
	ds_write_b32 v86, v107
	ds_write_b32 v88, v108
	ds_write_b32 v90, v109
	ds_write_b32 v92, v110
	ds_write_b32 v94, v111
	ds_write_b32 v96, v112
	s_cbranch_scc1 .LBB0_567
	s_waitcnt lgkmcnt(0)
	ds_read2_b32 v[42:43], v60 offset1:33
	s_lshl_b32 s18, s1, 1
	v_lshl_add_u64 v[48:49], v[12:13], 0, s[18:19]
	s_movk_i32 s1, 0x300
	s_waitcnt lgkmcnt(0)
	v_mul_f32_e32 v41, 0x3dd53b94, v42
	v_mul_f32_e32 v42, 0x3dd53b94, v43
	v_cvt_pk_bf16_f32 v42, v41, v42
	ds_read2_b32 v[44:45], v60 offset0:66 offset1:99
	s_waitcnt lgkmcnt(0)
	v_mul_f32_e32 v43, 0x3dd53b94, v45
	v_mul_f32_e32 v41, 0x3dd53b94, v44
	v_cvt_pk_bf16_f32 v43, v41, v43
	ds_read2_b32 v[44:45], v60 offset0:132 offset1:165
	s_waitcnt lgkmcnt(0)
	v_mul_f32_e32 v41, 0x3dd53b94, v44
	v_mul_f32_e32 v44, 0x3dd53b94, v45
	v_cvt_pk_bf16_f32 v44, v41, v44
	ds_read2_b32 v[46:47], v60 offset0:198 offset1:231
	v_add_u32_e32 v41, s0, v59
	v_mad_i64_i32 v[50:51], s[4:5], v41, s1, v[48:49]
	s_waitcnt lgkmcnt(0)
	v_mul_f32_e32 v45, 0x3dd53b94, v46
	v_mul_f32_e32 v46, 0x3dd53b94, v47
	v_cvt_pk_bf16_f32 v45, v45, v46
	ds_read2_b32 v[46:47], v60 offset0:8 offset1:41
	global_store_dwordx4 v[50:51], v[42:45], off
	s_waitcnt lgkmcnt(0)
	v_mul_f32_e32 v41, 0x3dd53b94, v46
	v_mul_f32_e32 v42, 0x3dd53b94, v47
	v_cvt_pk_bf16_f32 v42, v41, v42
	ds_read2_b32 v[44:45], v60 offset0:74 offset1:107
	s_waitcnt lgkmcnt(0)
	v_mul_f32_e32 v43, 0x3dd53b94, v45
	v_mul_f32_e32 v41, 0x3dd53b94, v44
	v_cvt_pk_bf16_f32 v43, v41, v43
	ds_read2_b32 v[44:45], v60 offset0:140 offset1:173
	s_waitcnt lgkmcnt(0)
	v_mul_f32_e32 v41, 0x3dd53b94, v44
	v_mul_f32_e32 v44, 0x3dd53b94, v45
	v_cvt_pk_bf16_f32 v44, v41, v44
	ds_read2_b32 v[46:47], v60 offset0:206 offset1:239
	s_waitcnt lgkmcnt(0)
	v_mul_f32_e32 v45, 0x3dd53b94, v47
	v_mul_f32_e32 v41, 0x3dd53b94, v46
	v_cvt_pk_bf16_f32 v45, v41, v45
	ds_read2_b32 v[46:47], v60 offset0:16 offset1:49
	v_add_u32_e32 v41, s0, v61
	v_mad_i64_i32 v[50:51], s[4:5], v41, s1, v[48:49]
	global_store_dwordx4 v[50:51], v[42:45], off
	s_waitcnt lgkmcnt(0)
	v_mul_f32_e32 v41, 0x3dd53b94, v46
	v_mul_f32_e32 v42, 0x3dd53b94, v47
	v_cvt_pk_bf16_f32 v42, v41, v42
	ds_read2_b32 v[44:45], v60 offset0:82 offset1:115
	s_waitcnt lgkmcnt(0)
	v_mul_f32_e32 v43, 0x3dd53b94, v45
	v_mul_f32_e32 v41, 0x3dd53b94, v44
	v_cvt_pk_bf16_f32 v43, v41, v43
	ds_read2_b32 v[44:45], v60 offset0:148 offset1:181
	s_waitcnt lgkmcnt(0)
	v_mul_f32_e32 v41, 0x3dd53b94, v44
	v_mul_f32_e32 v44, 0x3dd53b94, v45
	v_cvt_pk_bf16_f32 v44, v41, v44
	ds_read2_b32 v[46:47], v60 offset0:214 offset1:247
	s_waitcnt lgkmcnt(0)
	v_mul_f32_e32 v45, 0x3dd53b94, v47
	v_mul_f32_e32 v41, 0x3dd53b94, v46
	v_cvt_pk_bf16_f32 v45, v41, v45
	ds_read2_b32 v[46:47], v60 offset0:24 offset1:57
	v_add_u32_e32 v41, s0, v62
	v_mad_i64_i32 v[50:51], s[4:5], v41, s1, v[48:49]
	global_store_dwordx4 v[50:51], v[42:45], off
	s_waitcnt lgkmcnt(0)
	v_mul_f32_e32 v41, 0x3dd53b94, v46
	v_mul_f32_e32 v42, 0x3dd53b94, v47
	v_cvt_pk_bf16_f32 v42, v41, v42
	ds_read2_b32 v[44:45], v60 offset0:90 offset1:123
	s_waitcnt lgkmcnt(0)
	v_mul_f32_e32 v43, 0x3dd53b94, v45
	v_mul_f32_e32 v41, 0x3dd53b94, v44
	v_cvt_pk_bf16_f32 v43, v41, v43
	ds_read2_b32 v[44:45], v60 offset0:156 offset1:189
	s_waitcnt lgkmcnt(0)
	v_mul_f32_e32 v41, 0x3dd53b94, v44
	v_mul_f32_e32 v44, 0x3dd53b94, v45
	v_cvt_pk_bf16_f32 v44, v41, v44
	ds_read2_b32 v[46:47], v60 offset0:222 offset1:255
	v_add_u32_e32 v41, s0, v63
	s_waitcnt lgkmcnt(0)
	v_mul_f32_e32 v45, 0x3dd53b94, v46
	v_mul_f32_e32 v46, 0x3dd53b94, v47
	v_cvt_pk_bf16_f32 v45, v45, v46
	v_mad_i64_i32 v[46:47], s[0:1], v41, s1, v[48:49]
	global_store_dwordx4 v[46:47], v[42:45], off
	s_waitcnt lgkmcnt(0)

.LBB0_571:
	s_lshl_b32 s9, s5, 1
	s_lshl_b32 s10, s1, 1
	v_add_u32_e32 v64, s9, v44
	v_add_u32_e32 v66, s10, v41
	v_mad_i64_i32 v[64:65], s[14:15], v64, s76, v[42:43]
	v_add_u32_e32 v68, s9, v46
	v_add_u32_e32 v82, s9, v52
	v_mad_i64_i32 v[66:67], s[14:15], v66, s76, v[42:43]
	global_load_dword v89, v[64:65], off nt
	v_add_u32_e32 v70, s10, v45
	v_add_u32_e32 v80, s10, v51
	v_mad_i64_i32 v[68:69], s[14:15], v68, s76, v[42:43]
	v_mad_i64_i32 v[64:65], s[14:15], v82, s76, v[42:43]
	global_load_dword v82, v[66:67], off nt
	v_add_u32_e32 v72, s9, v48
	v_add_u32_e32 v84, s9, v54
	v_mad_i64_i32 v[70:71], s[14:15], v70, s76, v[42:43]
	v_mad_i64_i32 v[66:67], s[14:15], v80, s76, v[42:43]
	global_load_dword v80, v[68:69], off nt
	v_add_u32_e32 v74, s10, v47
	v_add_u32_e32 v83, s10, v53
	v_mad_i64_i32 v[72:73], s[14:15], v72, s76, v[42:43]
	v_mad_i64_i32 v[68:69], s[14:15], v84, s76, v[42:43]
	global_load_dword v84, v[70:71], off nt
	v_add_u32_e32 v78, s10, v49
	v_add_u32_e32 v76, s9, v50
	v_add_u32_e32 v86, s9, v56
	v_mad_i64_i32 v[74:75], s[14:15], v74, s76, v[42:43]
	v_mad_i64_i32 v[70:71], s[14:15], v83, s76, v[42:43]
	global_load_dword v83, v[72:73], off nt
	v_add_u32_e32 v85, s10, v55
	v_add_u32_e32 v87, s10, v57
	v_add_u32_e32 v88, s9, v58
	v_mad_i64_i32 v[76:77], s[14:15], v76, s76, v[42:43]
	v_mad_i64_i32 v[78:79], s[14:15], v78, s76, v[42:43]
	v_mad_i64_i32 v[72:73], s[14:15], v86, s76, v[42:43]
	global_load_dword v86, v[74:75], off nt
	v_mad_i64_i32 v[74:75], s[14:15], v85, s76, v[42:43]
	global_load_dword v85, v[76:77], off nt
	v_mad_i64_i32 v[76:77], s[14:15], v88, s76, v[42:43]
	global_load_dword v88, v[78:79], off nt
	v_mad_i64_i32 v[78:79], s[14:15], v87, s76, v[42:43]
	global_load_dword v87, v[64:65], off nt
	global_load_dword v90, v[66:67], off nt
	global_load_dword v91, v[68:69], off nt
	global_load_dword v92, v[70:71], off nt
	global_load_dword v93, v[72:73], off nt
	global_load_dword v94, v[74:75], off nt
	global_load_dword v95, v[76:77], off nt
	global_load_dword v96, v[78:79], off nt
	v_add_u32_e32 v64, s9, v0
	v_add_u32_e32 v66, s10, v1
	v_mad_u64_u32 v[64:65], s[14:15], v64, s73, v[2:3]
	v_add_u32_e32 v68, s9, v28
	v_add_u32_e32 v67, s10, v3
	v_add_u32_e32 v70, s9, v30
	v_add_u32_e32 v69, s10, v29
	v_add_u32_e32 v71, s10, v31
	v_add_u32_e32 v73, s10, v33
	v_add_u32_e32 v75, s10, v35
	v_add_u32_e32 v77, s10, v37
	v_add_u32_e32 v79, s10, v39
	s_add_i32 s5, s5, 16
	s_add_i32 s1, s1, 16
	s_add_i32 s8, s8, -16
	v_add_u32_e32 v72, s9, v32
	v_add_u32_e32 v74, s9, v34
	v_add_u32_e32 v76, s9, v36
	v_add_u32_e32 v78, s9, v38
	s_cmp_lg_u32 s8, 0
	s_waitcnt vmcnt(0)
	ds_write_b32 v64, v89
	v_mad_u64_u32 v[64:65], s[14:15], v66, s73, v[2:3]
	ds_write_b32 v64, v82
	v_mad_u64_u32 v[64:65], s[14:15], v68, s73, v[2:3]
	ds_write_b32 v64, v80
	v_mad_u64_u32 v[64:65], s[14:15], v67, s73, v[2:3]
	v_add_u32_e32 v80, s9, v40
	v_mad_u64_u32 v[66:67], s[10:11], v72, s73, v[2:3]
	ds_write_b32 v64, v84
	v_mad_u64_u32 v[64:65], s[10:11], v70, s73, v[2:3]
	ds_write_b32 v64, v83
	v_mad_u64_u32 v[64:65], s[10:11], v69, s73, v[2:3]
	v_mad_u64_u32 v[68:69], s[10:11], v74, s73, v[2:3]
	ds_write_b32 v64, v86
	v_mad_u64_u32 v[64:65], s[10:11], v71, s73, v[2:3]
	v_mad_u64_u32 v[70:71], s[10:11], v73, s73, v[2:3]
	ds_write_b32 v66, v85
	v_mad_u64_u32 v[66:67], s[10:11], v76, s73, v[2:3]
	v_mad_u64_u32 v[72:73], s[10:11], v75, s73, v[2:3]
	v_mad_u64_u32 v[74:75], s[10:11], v78, s73, v[2:3]
	ds_write_b32 v64, v88
	v_mad_u64_u32 v[64:65], s[10:11], v77, s73, v[2:3]
	v_mad_u64_u32 v[76:77], s[10:11], v80, s73, v[2:3]
	v_mad_u64_u32 v[78:79], s[10:11], v79, s73, v[2:3]
	ds_write_b32 v68, v87
	ds_write_b32 v70, v90
	ds_write_b32 v66, v91
	ds_write_b32 v72, v92
	ds_write_b32 v74, v93
	ds_write_b32 v64, v94
	ds_write_b32 v76, v95
	ds_write_b32 v78, v96
	s_cbranch_scc1 .LBB0_571
	s_waitcnt lgkmcnt(0)
	v_add_u32_e32 v48, s0, v59
	ds_read2_b32 v[42:43], v60 offset1:33
	s_ashr_i32 s5, s4, 31
	v_ashrrev_i32_e32 v49, 31, v48
	s_waitcnt lgkmcnt(0)
	v_cvt_pk_bf16_f32 v42, v42, v43
	ds_read2_b32 v[44:45], v60 offset0:66 offset1:99
	v_lshl_add_u64 v[50:51], s[4:5], 1, v[14:15]
	v_lshlrev_b64 v[48:49], 11, v[48:49]
	s_waitcnt lgkmcnt(0)
	v_cvt_pk_bf16_f32 v43, v44, v45
	ds_read2_b32 v[44:45], v60 offset0:132 offset1:165
	v_lshl_add_u64 v[48:49], v[50:51], 0, v[48:49]
	s_waitcnt lgkmcnt(0)
	v_cvt_pk_bf16_f32 v44, v44, v45
	ds_read2_b32 v[46:47], v60 offset0:198 offset1:231
	s_waitcnt lgkmcnt(0)
	v_cvt_pk_bf16_f32 v45, v46, v47
	global_store_dwordx4 v[48:49], v[42:45], off
	v_add_u32_e32 v48, s0, v61
	v_ashrrev_i32_e32 v49, 31, v48
	ds_read2_b32 v[46:47], v60 offset0:8 offset1:41
	s_waitcnt lgkmcnt(0)
	v_cvt_pk_bf16_f32 v42, v46, v47
	ds_read2_b32 v[44:45], v60 offset0:74 offset1:107
	v_lshlrev_b64 v[48:49], 11, v[48:49]
	s_waitcnt lgkmcnt(0)
	v_cvt_pk_bf16_f32 v43, v44, v45
	ds_read2_b32 v[44:45], v60 offset0:140 offset1:173
	v_lshl_add_u64 v[48:49], v[50:51], 0, v[48:49]
	s_waitcnt lgkmcnt(0)
	v_cvt_pk_bf16_f32 v44, v44, v45
	ds_read2_b32 v[46:47], v60 offset0:206 offset1:239
	s_waitcnt lgkmcnt(0)
	v_cvt_pk_bf16_f32 v45, v46, v47
	global_store_dwordx4 v[48:49], v[42:45], off
	v_add_u32_e32 v48, s0, v62
	ds_read2_b32 v[46:47], v60 offset0:16 offset1:49
	s_waitcnt lgkmcnt(0)
	v_cvt_pk_bf16_f32 v42, v46, v47
	ds_read2_b32 v[44:45], v60 offset0:82 offset1:115
	v_ashrrev_i32_e32 v49, 31, v48
	s_waitcnt lgkmcnt(0)
	v_cvt_pk_bf16_f32 v43, v44, v45
	ds_read2_b32 v[44:45], v60 offset0:148 offset1:181
	v_lshlrev_b64 v[48:49], 11, v[48:49]
	s_waitcnt lgkmcnt(0)
	v_cvt_pk_bf16_f32 v44, v44, v45
	ds_read2_b32 v[46:47], v60 offset0:214 offset1:247
	s_waitcnt lgkmcnt(0)
	v_cvt_pk_bf16_f32 v45, v46, v47
	v_lshl_add_u64 v[48:49], v[50:51], 0, v[48:49]
	ds_read2_b32 v[46:47], v60 offset0:24 offset1:57
	global_store_dwordx4 v[48:49], v[42:45], off
	v_add_u32_e32 v48, s0, v63
	v_ashrrev_i32_e32 v49, 31, v48
	s_waitcnt lgkmcnt(0)
	v_cvt_pk_bf16_f32 v42, v46, v47
	ds_read2_b32 v[44:45], v60 offset0:90 offset1:123
	s_waitcnt lgkmcnt(0)
	v_cvt_pk_bf16_f32 v43, v44, v45
	ds_read2_b32 v[44:45], v60 offset0:156 offset1:189
	s_waitcnt lgkmcnt(0)
	v_cvt_pk_bf16_f32 v44, v44, v45
	ds_read2_b32 v[46:47], v60 offset0:222 offset1:255
	v_lshlrev_b64 v[48:49], 11, v[48:49]
	s_waitcnt lgkmcnt(0)
	v_cvt_pk_bf16_f32 v45, v46, v47
	v_lshl_add_u64 v[46:47], v[50:51], 0, v[48:49]
	global_store_dwordx4 v[46:47], v[42:45], off
	s_waitcnt lgkmcnt(0)
	s_branch .LBB0_540
